# K-loop setprio flips removed; one static s_setprio 1 for waves 4-7 at GEMM1 entry
# speedup vs baseline: 1.0048x; 1.0048x over previous
.LBB0_212:
	s_cmp_lt_u32 s62, 4
	s_cbranch_scc1 .Lprio_skip
	s_setprio 1

.LBB0_228:
	ds_read_b128 v[128:131], v179
	ds_read_b128 v[132:135], v179 offset:1024
	ds_read_b128 v[136:139], v179 offset:2048
	ds_read_b128 v[140:143], v179 offset:3072
	ds_read_b128 v[162:165], v180
	ds_read_b128 v[166:169], v180 offset:1024
	ds_read_b128 v[170:173], v180 offset:2048
	ds_read_b128 v[186:189], v180 offset:3072
	s_add_u32 s8, s6, 0x10000
	s_addc_u32 s9, s7, 0
	s_cmp_eq_u32 s92, 12
	s_cselect_b32 s80, s69, s8
	s_cselect_b32 s81, s18, s9
	s_cselect_b32 s12, s77, vcc_lo
	s_cselect_b32 s13, s71, vcc_hi
	s_add_u32 s10, s80, 0x8000
	s_addc_u32 s11, s81, 0
	s_add_i32 m0, s79, 0xc000
	ds_read_b128 v[190:193], v181
	ds_read_b128 v[194:197], v181 offset:1024
	ds_read_b128 v[198:201], v181 offset:2048
	ds_read_b128 v[202:205], v181 offset:3072
	ds_read_b128 v[206:209], v181 offset:4096
	ds_read_b128 v[210:213], v181 offset:5120
	ds_read_b128 v[214:217], v181 offset:6144
	ds_read_b128 v[218:221], v181 offset:7168
	global_load_lds_dwordx4 v154, s[6:7]
	s_add_i32 m0, s79, 0xe000
	s_nop 0
	global_load_lds_dwordx4 v156, s[6:7]
	s_waitcnt vmcnt(8)
	s_waitcnt lgkmcnt(0)
	s_barrier
	s_waitcnt lgkmcnt(0)
	v_mfma_f32_16x16x32_bf16 v[124:127], v[128:131], v[190:193], v[124:127]
	v_mfma_f32_16x16x32_bf16 v[120:123], v[136:139], v[190:193], v[120:123]
	v_mfma_f32_16x16x32_bf16 v[108:111], v[128:131], v[198:201], v[108:111]
	v_mfma_f32_16x16x32_bf16 v[104:107], v[136:139], v[198:201], v[104:107]
	v_mfma_f32_16x16x32_bf16 v[92:95], v[128:131], v[206:209], v[92:95]
	v_mfma_f32_16x16x32_bf16 v[88:91], v[136:139], v[206:209], v[88:91]
	v_mfma_f32_16x16x32_bf16 v[76:79], v[128:131], v[214:217], v[76:79]
	v_mfma_f32_16x16x32_bf16 v[72:75], v[136:139], v[214:217], v[72:75]
	v_mfma_f32_16x16x32_bf16 v[124:127], v[132:135], v[194:197], v[124:127]
	v_mfma_f32_16x16x32_bf16 v[120:123], v[140:143], v[194:197], v[120:123]
	v_mfma_f32_16x16x32_bf16 v[108:111], v[132:135], v[202:205], v[108:111]
	v_mfma_f32_16x16x32_bf16 v[104:107], v[140:143], v[202:205], v[104:107]
	v_mfma_f32_16x16x32_bf16 v[92:95], v[132:135], v[210:213], v[92:95]
	v_mfma_f32_16x16x32_bf16 v[88:91], v[140:143], v[210:213], v[88:91]
	v_mfma_f32_16x16x32_bf16 v[76:79], v[132:135], v[218:221], v[76:79]
	v_mfma_f32_16x16x32_bf16 v[72:75], v[140:143], v[218:221], v[72:75]
	v_mfma_f32_16x16x32_bf16 v[116:119], v[162:165], v[190:193], v[116:119]
	v_mfma_f32_16x16x32_bf16 v[112:115], v[170:173], v[190:193], v[112:115]
	v_mfma_f32_16x16x32_bf16 v[100:103], v[162:165], v[198:201], v[100:103]
	v_mfma_f32_16x16x32_bf16 v[96:99], v[170:173], v[198:201], v[96:99]
	v_mfma_f32_16x16x32_bf16 v[84:87], v[162:165], v[206:209], v[84:87]
	v_mfma_f32_16x16x32_bf16 v[80:83], v[170:173], v[206:209], v[80:83]
	v_mfma_f32_16x16x32_bf16 v[68:71], v[162:165], v[214:217], v[68:71]
	v_mfma_f32_16x16x32_bf16 v[64:67], v[170:173], v[214:217], v[64:67]
	v_mfma_f32_16x16x32_bf16 v[116:119], v[166:169], v[194:197], v[116:119]
	v_mfma_f32_16x16x32_bf16 v[112:115], v[186:189], v[194:197], v[112:115]
	v_mfma_f32_16x16x32_bf16 v[100:103], v[166:169], v[202:205], v[100:103]
	v_mfma_f32_16x16x32_bf16 v[96:99], v[186:189], v[202:205], v[96:99]
	v_mfma_f32_16x16x32_bf16 v[84:87], v[166:169], v[210:213], v[84:87]
	v_mfma_f32_16x16x32_bf16 v[80:83], v[186:189], v[210:213], v[80:83]
	v_mfma_f32_16x16x32_bf16 v[68:71], v[166:169], v[218:221], v[68:71]
	v_mfma_f32_16x16x32_bf16 v[64:67], v[186:189], v[218:221], v[64:67]
	s_barrier
	s_add_i32 s6, s34, s84
	s_mov_b32 m0, s6
	ds_read_b128 v[190:193], v181 offset:16384
	ds_read_b128 v[194:197], v181 offset:17408
	ds_read_b128 v[198:201], v181 offset:18432
	ds_read_b128 v[202:205], v181 offset:19456
	ds_read_b128 v[206:209], v181 offset:20480
	ds_read_b128 v[210:213], v181 offset:21504
	ds_read_b128 v[214:217], v181 offset:22528
	ds_read_b128 v[218:221], v181 offset:23552
	global_load_lds_dwordx4 v146, s[12:13]
	s_add_i32 m0, s6, 0x2000
	s_add_u32 s6, s12, 0x40000
	s_addc_u32 s7, s13, 0
	s_add_i32 s38, s35, s84
	global_load_lds_dwordx4 v150, s[12:13]
	s_mov_b32 m0, s38
	s_nop 0
	global_load_lds_dwordx4 v146, s[6:7]
	s_add_i32 m0, s38, 0x2000
	s_nop 0
	global_load_lds_dwordx4 v150, s[6:7]
	s_mov_b32 m0, s79
	s_nop 0
	global_load_lds_dwordx4 v144, s[80:81]
	s_mov_b32 m0, s85
	s_nop 0
	global_load_lds_dwordx4 v148, s[80:81]
	s_waitcnt vmcnt(8)
	s_waitcnt lgkmcnt(0)
	s_barrier
	s_waitcnt lgkmcnt(0)
	v_mfma_f32_16x16x32_bf16 v[60:63], v[128:131], v[190:193], v[60:63]
	v_mfma_f32_16x16x32_bf16 v[56:59], v[136:139], v[190:193], v[56:59]
	v_mfma_f32_16x16x32_bf16 v[44:47], v[128:131], v[198:201], v[44:47]
	v_mfma_f32_16x16x32_bf16 v[40:43], v[136:139], v[198:201], v[40:43]
	v_mfma_f32_16x16x32_bf16 v[28:31], v[128:131], v[206:209], v[28:31]
	v_mfma_f32_16x16x32_bf16 v[24:27], v[136:139], v[206:209], v[24:27]
	v_mfma_f32_16x16x32_bf16 v[12:15], v[128:131], v[214:217], v[12:15]
	v_mfma_f32_16x16x32_bf16 v[8:11], v[136:139], v[214:217], v[8:11]
	v_mfma_f32_16x16x32_bf16 v[60:63], v[132:135], v[194:197], v[60:63]
	v_mfma_f32_16x16x32_bf16 v[56:59], v[140:143], v[194:197], v[56:59]
	v_mfma_f32_16x16x32_bf16 v[44:47], v[132:135], v[202:205], v[44:47]
	v_mfma_f32_16x16x32_bf16 v[40:43], v[140:143], v[202:205], v[40:43]
	v_mfma_f32_16x16x32_bf16 v[28:31], v[132:135], v[210:213], v[28:31]
	v_mfma_f32_16x16x32_bf16 v[24:27], v[140:143], v[210:213], v[24:27]
	v_mfma_f32_16x16x32_bf16 v[12:15], v[132:135], v[218:221], v[12:15]
	v_mfma_f32_16x16x32_bf16 v[8:11], v[140:143], v[218:221], v[8:11]
	v_mfma_f32_16x16x32_bf16 v[52:55], v[162:165], v[190:193], v[52:55]
	v_mfma_f32_16x16x32_bf16 v[48:51], v[170:173], v[190:193], v[48:51]
	v_mfma_f32_16x16x32_bf16 v[36:39], v[162:165], v[198:201], v[36:39]
	v_mfma_f32_16x16x32_bf16 v[32:35], v[170:173], v[198:201], v[32:35]
	v_mfma_f32_16x16x32_bf16 v[20:23], v[162:165], v[206:209], v[20:23]
	v_mfma_f32_16x16x32_bf16 v[16:19], v[170:173], v[206:209], v[16:19]
	v_mfma_f32_16x16x32_bf16 v[4:7], v[162:165], v[214:217], v[4:7]
	v_mfma_f32_16x16x32_bf16 v[0:3], v[170:173], v[214:217], v[0:3]
	v_mfma_f32_16x16x32_bf16 v[52:55], v[166:169], v[194:197], v[52:55]
	v_mfma_f32_16x16x32_bf16 v[48:51], v[186:189], v[194:197], v[48:51]
	v_mfma_f32_16x16x32_bf16 v[36:39], v[166:169], v[202:205], v[36:39]
	v_mfma_f32_16x16x32_bf16 v[32:35], v[186:189], v[202:205], v[32:35]
	v_mfma_f32_16x16x32_bf16 v[20:23], v[166:169], v[210:213], v[20:23]
	v_mfma_f32_16x16x32_bf16 v[16:19], v[186:189], v[210:213], v[16:19]
	v_mfma_f32_16x16x32_bf16 v[4:7], v[166:169], v[218:221], v[4:7]
	v_mfma_f32_16x16x32_bf16 v[0:3], v[186:189], v[218:221], v[0:3]
	s_barrier
	s_add_i32 s38, 0, 0x18000
	s_add_i32 s39, 0, 0x1c000
	v_add_u32_e32 v140, s38, v178
	v_add_u32_e32 v152, s39, v178
	ds_read_b128 v[128:131], v140
	ds_read_b128 v[132:135], v140 offset:1024
	ds_read_b128 v[136:139], v140 offset:2048
	ds_read_b128 v[140:143], v140 offset:3072
	ds_read_b128 v[162:165], v152
	ds_read_b128 v[166:169], v152 offset:1024
	ds_read_b128 v[170:173], v152 offset:2048
	ds_read_b128 v[186:189], v152 offset:3072
	s_add_u32 s6, s80, 0x4000
	s_addc_u32 s7, s81, 0
	s_mov_b32 m0, s86
	ds_read_b128 v[190:193], v181 offset:32768
	ds_read_b128 v[194:197], v181 offset:33792
	ds_read_b128 v[198:201], v181 offset:34816
	ds_read_b128 v[202:205], v181 offset:35840
	ds_read_b128 v[206:209], v181 offset:36864
	ds_read_b128 v[210:213], v181 offset:37888
	ds_read_b128 v[214:217], v181 offset:38912
	ds_read_b128 v[218:221], v181 offset:39936
	global_load_lds_dwordx4 v144, s[6:7]
	s_mov_b32 m0, s87
	s_nop 0
	global_load_lds_dwordx4 v148, s[6:7]
	s_waitcnt vmcnt(8)
	s_waitcnt lgkmcnt(0)
	s_barrier
	s_waitcnt lgkmcnt(0)
	v_mfma_f32_16x16x32_bf16 v[124:127], v[128:131], v[190:193], v[124:127]
	v_mfma_f32_16x16x32_bf16 v[120:123], v[136:139], v[190:193], v[120:123]
	v_mfma_f32_16x16x32_bf16 v[108:111], v[128:131], v[198:201], v[108:111]
	v_mfma_f32_16x16x32_bf16 v[104:107], v[136:139], v[198:201], v[104:107]
	v_mfma_f32_16x16x32_bf16 v[92:95], v[128:131], v[206:209], v[92:95]
	v_mfma_f32_16x16x32_bf16 v[88:91], v[136:139], v[206:209], v[88:91]
	v_mfma_f32_16x16x32_bf16 v[76:79], v[128:131], v[214:217], v[76:79]
	v_mfma_f32_16x16x32_bf16 v[72:75], v[136:139], v[214:217], v[72:75]
	v_mfma_f32_16x16x32_bf16 v[124:127], v[132:135], v[194:197], v[124:127]
	v_mfma_f32_16x16x32_bf16 v[120:123], v[140:143], v[194:197], v[120:123]
	v_mfma_f32_16x16x32_bf16 v[108:111], v[132:135], v[202:205], v[108:111]
	v_mfma_f32_16x16x32_bf16 v[104:107], v[140:143], v[202:205], v[104:107]
	v_mfma_f32_16x16x32_bf16 v[92:95], v[132:135], v[210:213], v[92:95]
	v_mfma_f32_16x16x32_bf16 v[88:91], v[140:143], v[210:213], v[88:91]
	v_mfma_f32_16x16x32_bf16 v[76:79], v[132:135], v[218:221], v[76:79]
	v_mfma_f32_16x16x32_bf16 v[72:75], v[140:143], v[218:221], v[72:75]
	v_mfma_f32_16x16x32_bf16 v[116:119], v[162:165], v[190:193], v[116:119]
	v_mfma_f32_16x16x32_bf16 v[112:115], v[170:173], v[190:193], v[112:115]
	v_mfma_f32_16x16x32_bf16 v[100:103], v[162:165], v[198:201], v[100:103]
	v_mfma_f32_16x16x32_bf16 v[96:99], v[170:173], v[198:201], v[96:99]
	v_mfma_f32_16x16x32_bf16 v[84:87], v[162:165], v[206:209], v[84:87]
	v_mfma_f32_16x16x32_bf16 v[80:83], v[170:173], v[206:209], v[80:83]
	v_mfma_f32_16x16x32_bf16 v[68:71], v[162:165], v[214:217], v[68:71]
	v_mfma_f32_16x16x32_bf16 v[64:67], v[170:173], v[214:217], v[64:67]
	v_mfma_f32_16x16x32_bf16 v[116:119], v[166:169], v[194:197], v[116:119]
	v_mfma_f32_16x16x32_bf16 v[112:115], v[186:189], v[194:197], v[112:115]
	v_mfma_f32_16x16x32_bf16 v[100:103], v[166:169], v[202:205], v[100:103]
	v_mfma_f32_16x16x32_bf16 v[96:99], v[186:189], v[202:205], v[96:99]
	v_mfma_f32_16x16x32_bf16 v[84:87], v[166:169], v[210:213], v[84:87]
	v_mfma_f32_16x16x32_bf16 v[80:83], v[186:189], v[210:213], v[80:83]
	v_mfma_f32_16x16x32_bf16 v[68:71], v[166:169], v[218:221], v[68:71]
	v_mfma_f32_16x16x32_bf16 v[64:67], v[186:189], v[218:221], v[64:67]
	s_barrier
	s_add_u32 s98, s12, s48
	s_addc_u32 s99, s13, s49
	s_add_i32 s6, s38, s84
	s_mov_b32 m0, s6
	ds_read_b128 v[190:193], v181 offset:49152
	ds_read_b128 v[194:197], v181 offset:50176
	ds_read_b128 v[198:201], v181 offset:51200
	ds_read_b128 v[202:205], v181 offset:52224
	ds_read_b128 v[206:209], v181 offset:53248
	ds_read_b128 v[210:213], v181 offset:54272
	ds_read_b128 v[214:217], v181 offset:55296
	ds_read_b128 v[218:221], v181 offset:56320
	global_load_lds_dwordx4 v146, s[98:99]
	s_add_i32 m0, s6, 0x2000
	s_add_u32 s6, s12, 0x40080
	s_addc_u32 s7, s13, 0
	s_add_i32 s12, s39, s84
	global_load_lds_dwordx4 v150, s[98:99]
	s_mov_b32 m0, s12
	s_nop 0
	global_load_lds_dwordx4 v146, s[6:7]
	s_add_i32 m0, s12, 0x2000
	s_nop 0
	global_load_lds_dwordx4 v150, s[6:7]
	s_mov_b32 m0, s33
	s_nop 0
	global_load_lds_dwordx4 v144, s[10:11]
	s_mov_b32 m0, s56
	s_nop 0
	global_load_lds_dwordx4 v148, s[10:11]
	s_waitcnt vmcnt(8)
	s_waitcnt lgkmcnt(0)
	s_barrier
	s_waitcnt lgkmcnt(0)
	v_mfma_f32_16x16x32_bf16 v[60:63], v[128:131], v[190:193], v[60:63]
	v_mfma_f32_16x16x32_bf16 v[56:59], v[136:139], v[190:193], v[56:59]
	v_mfma_f32_16x16x32_bf16 v[44:47], v[128:131], v[198:201], v[44:47]
	v_mfma_f32_16x16x32_bf16 v[40:43], v[136:139], v[198:201], v[40:43]
	v_mfma_f32_16x16x32_bf16 v[28:31], v[128:131], v[206:209], v[28:31]
	v_mfma_f32_16x16x32_bf16 v[24:27], v[136:139], v[206:209], v[24:27]
	v_mfma_f32_16x16x32_bf16 v[12:15], v[128:131], v[214:217], v[12:15]
	v_mfma_f32_16x16x32_bf16 v[8:11], v[136:139], v[214:217], v[8:11]
	v_mfma_f32_16x16x32_bf16 v[60:63], v[132:135], v[194:197], v[60:63]
	v_mfma_f32_16x16x32_bf16 v[56:59], v[140:143], v[194:197], v[56:59]
	v_mfma_f32_16x16x32_bf16 v[44:47], v[132:135], v[202:205], v[44:47]
	v_mfma_f32_16x16x32_bf16 v[40:43], v[140:143], v[202:205], v[40:43]
	v_mfma_f32_16x16x32_bf16 v[28:31], v[132:135], v[210:213], v[28:31]
	v_mfma_f32_16x16x32_bf16 v[24:27], v[140:143], v[210:213], v[24:27]
	v_mfma_f32_16x16x32_bf16 v[12:15], v[132:135], v[218:221], v[12:15]
	v_mfma_f32_16x16x32_bf16 v[8:11], v[140:143], v[218:221], v[8:11]
	v_mfma_f32_16x16x32_bf16 v[52:55], v[162:165], v[190:193], v[52:55]
	v_mfma_f32_16x16x32_bf16 v[48:51], v[170:173], v[190:193], v[48:51]
	v_mfma_f32_16x16x32_bf16 v[36:39], v[162:165], v[198:201], v[36:39]
	v_mfma_f32_16x16x32_bf16 v[32:35], v[170:173], v[198:201], v[32:35]
	v_mfma_f32_16x16x32_bf16 v[20:23], v[162:165], v[206:209], v[20:23]
	v_mfma_f32_16x16x32_bf16 v[16:19], v[170:173], v[206:209], v[16:19]
	v_mfma_f32_16x16x32_bf16 v[4:7], v[162:165], v[214:217], v[4:7]
	v_mfma_f32_16x16x32_bf16 v[0:3], v[170:173], v[214:217], v[0:3]
	v_mfma_f32_16x16x32_bf16 v[52:55], v[166:169], v[194:197], v[52:55]
	v_mfma_f32_16x16x32_bf16 v[48:51], v[186:189], v[194:197], v[48:51]
	v_mfma_f32_16x16x32_bf16 v[36:39], v[166:169], v[202:205], v[36:39]
	v_mfma_f32_16x16x32_bf16 v[32:35], v[186:189], v[202:205], v[32:35]
	v_mfma_f32_16x16x32_bf16 v[20:23], v[166:169], v[210:213], v[20:23]
	v_mfma_f32_16x16x32_bf16 v[16:19], v[186:189], v[210:213], v[16:19]
	v_mfma_f32_16x16x32_bf16 v[4:7], v[166:169], v[218:221], v[4:7]
	v_mfma_f32_16x16x32_bf16 v[0:3], v[186:189], v[218:221], v[0:3]
	s_barrier
	s_add_i32 s92, s92, 2
	s_add_u32 vcc_lo, vcc_lo, 0x100
	s_addc_u32 vcc_hi, vcc_hi, 0
	s_cmp_gt_u32 s92, 13
	s_mov_b64 s[6:7], s[8:9]
	s_cbranch_scc0 .LBB0_228
	s_and_b64 vcc, exec, s[82:83]
	s_cbranch_vccz .LBB0_231
	s_barrier

.LBB0_448:
	v_add_u32_e32 v1, s78, v210
	ds_read_b128 v[132:135], v1
	ds_read_b128 v[136:139], v1 offset:1024
	ds_read_b128 v[140:143], v1 offset:2048
	ds_read_b128 v[144:147], v1 offset:3072
	v_add_u32_e32 v1, s79, v210
	s_add_u32 s48, s38, s46
	ds_read_b128 v[148:151], v1
	ds_read_b128 v[152:155], v1 offset:1024
	ds_read_b128 v[156:159], v1 offset:2048
	ds_read_b128 v[160:163], v1 offset:3072
	s_addc_u32 s49, s39, s47
	s_add_u32 s48, s48, 0x10000
	s_addc_u32 s49, s49, 0
	s_cmp_eq_u32 s46, 0xf0000
	s_cselect_b32 s64, s81, s48
	s_cselect_b32 s65, s21, s49
	s_cselect_b32 s50, s83, s41
	s_cselect_b32 s51, s19, s86
	s_add_u32 s48, s64, 0x8000
	s_addc_u32 s49, s65, 0
	v_lshl_add_u64 v[2:3], v[204:205], 0, s[46:47]
	s_add_i32 m0, s35, 0xc000
	ds_read_b128 v[164:167], v211
	ds_read_b128 v[168:171], v211 offset:1024
	ds_read_b128 v[172:175], v211 offset:2048
	ds_read_b128 v[176:179], v211 offset:3072
	ds_read_b128 v[180:183], v211 offset:4096
	ds_read_b128 v[184:187], v211 offset:5120
	ds_read_b128 v[212:215], v211 offset:6144
	ds_read_b128 v[216:219], v211 offset:7168
	global_load_lds_dwordx4 v[2:3], off
	v_lshl_add_u64 v[2:3], v[206:207], 0, s[46:47]
	s_add_i32 m0, s35, 0xe000
	s_nop 0
	global_load_lds_dwordx4 v[2:3], off
	s_waitcnt vmcnt(8)
	s_waitcnt lgkmcnt(0)
	s_barrier
	s_waitcnt lgkmcnt(0)
	v_mfma_f32_16x16x32_bf16 v[128:131], v[132:135], v[164:167], v[128:131]
	v_mfma_f32_16x16x32_bf16 v[124:127], v[140:143], v[164:167], v[124:127]
	v_mfma_f32_16x16x32_bf16 v[112:115], v[132:135], v[172:175], v[112:115]
	v_mfma_f32_16x16x32_bf16 v[108:111], v[140:143], v[172:175], v[108:111]
	v_mfma_f32_16x16x32_bf16 v[96:99], v[132:135], v[180:183], v[96:99]
	v_mfma_f32_16x16x32_bf16 v[92:95], v[140:143], v[180:183], v[92:95]
	v_mfma_f32_16x16x32_bf16 v[80:83], v[132:135], v[212:215], v[80:83]
	v_mfma_f32_16x16x32_bf16 v[76:79], v[140:143], v[212:215], v[76:79]
	v_mfma_f32_16x16x32_bf16 v[128:131], v[136:139], v[168:171], v[128:131]
	v_mfma_f32_16x16x32_bf16 v[124:127], v[144:147], v[168:171], v[124:127]
	v_mfma_f32_16x16x32_bf16 v[112:115], v[136:139], v[176:179], v[112:115]
	v_mfma_f32_16x16x32_bf16 v[108:111], v[144:147], v[176:179], v[108:111]
	v_mfma_f32_16x16x32_bf16 v[96:99], v[136:139], v[184:187], v[96:99]
	v_mfma_f32_16x16x32_bf16 v[92:95], v[144:147], v[184:187], v[92:95]
	v_mfma_f32_16x16x32_bf16 v[80:83], v[136:139], v[216:219], v[80:83]
	v_mfma_f32_16x16x32_bf16 v[76:79], v[144:147], v[216:219], v[76:79]
	v_mfma_f32_16x16x32_bf16 v[120:123], v[148:151], v[164:167], v[120:123]
	v_mfma_f32_16x16x32_bf16 v[116:119], v[156:159], v[164:167], v[116:119]
	v_mfma_f32_16x16x32_bf16 v[104:107], v[148:151], v[172:175], v[104:107]
	v_mfma_f32_16x16x32_bf16 v[100:103], v[156:159], v[172:175], v[100:103]
	v_mfma_f32_16x16x32_bf16 v[88:91], v[148:151], v[180:183], v[88:91]
	v_mfma_f32_16x16x32_bf16 v[84:87], v[156:159], v[180:183], v[84:87]
	v_mfma_f32_16x16x32_bf16 v[72:75], v[148:151], v[212:215], v[72:75]
	v_mfma_f32_16x16x32_bf16 v[68:71], v[156:159], v[212:215], v[68:71]
	v_mfma_f32_16x16x32_bf16 v[120:123], v[152:155], v[168:171], v[120:123]
	v_mfma_f32_16x16x32_bf16 v[116:119], v[160:163], v[168:171], v[116:119]
	v_mfma_f32_16x16x32_bf16 v[104:107], v[152:155], v[176:179], v[104:107]
	v_mfma_f32_16x16x32_bf16 v[100:103], v[160:163], v[176:179], v[100:103]
	v_mfma_f32_16x16x32_bf16 v[88:91], v[152:155], v[184:187], v[88:91]
	v_mfma_f32_16x16x32_bf16 v[84:87], v[160:163], v[184:187], v[84:87]
	v_mfma_f32_16x16x32_bf16 v[72:75], v[152:155], v[216:219], v[72:75]
	v_mfma_f32_16x16x32_bf16 v[68:71], v[160:163], v[216:219], v[68:71]
	s_barrier
	s_add_i32 s88, s78, s34
	s_mov_b32 m0, s88
	ds_read_b128 v[164:167], v211 offset:16384
	ds_read_b128 v[168:171], v211 offset:17408
	ds_read_b128 v[172:175], v211 offset:18432
	ds_read_b128 v[176:179], v211 offset:19456
	ds_read_b128 v[180:183], v211 offset:20480
	ds_read_b128 v[184:187], v211 offset:21504
	ds_read_b128 v[212:215], v211 offset:22528
	ds_read_b128 v[216:219], v211 offset:23552
	global_load_lds_dwordx4 v192, s[50:51]
	s_add_i32 m0, s88, 0x2000
	s_add_u32 s88, s50, 0x80000
	v_lshl_add_u64 v[222:223], s[50:51], 0, v[188:189]
	s_addc_u32 s89, s51, 0
	s_add_i32 s90, s79, s34
	global_load_lds_dwordx4 v[222:223], off
	s_mov_b32 m0, s90
	s_nop 0
	global_load_lds_dwordx4 v192, s[88:89]
	s_add_i32 m0, s90, 0x2000
	s_nop 0
	global_load_lds_dwordx4 v188, s[88:89]
	s_mov_b32 m0, s35
	s_nop 0
	global_load_lds_dwordx4 v194, s[64:65]
	s_mov_b32 m0, s56
	s_nop 0
	global_load_lds_dwordx4 v190, s[64:65]
	s_waitcnt vmcnt(8)
	s_waitcnt lgkmcnt(0)
	s_barrier
	s_waitcnt lgkmcnt(0)
	v_mfma_f32_16x16x32_bf16 v[64:67], v[132:135], v[164:167], v[64:67]
	v_mfma_f32_16x16x32_bf16 v[60:63], v[140:143], v[164:167], v[60:63]
	v_mfma_f32_16x16x32_bf16 v[48:51], v[132:135], v[172:175], v[48:51]
	v_mfma_f32_16x16x32_bf16 v[44:47], v[140:143], v[172:175], v[44:47]
	v_mfma_f32_16x16x32_bf16 v[32:35], v[132:135], v[180:183], v[32:35]
	v_mfma_f32_16x16x32_bf16 v[28:31], v[140:143], v[180:183], v[28:31]
	v_mfma_f32_16x16x32_bf16 v[16:19], v[132:135], v[212:215], v[16:19]
	v_mfma_f32_16x16x32_bf16 v[12:15], v[140:143], v[212:215], v[12:15]
	v_mfma_f32_16x16x32_bf16 v[64:67], v[136:139], v[168:171], v[64:67]
	v_mfma_f32_16x16x32_bf16 v[60:63], v[144:147], v[168:171], v[60:63]
	v_mfma_f32_16x16x32_bf16 v[48:51], v[136:139], v[176:179], v[48:51]
	v_mfma_f32_16x16x32_bf16 v[44:47], v[144:147], v[176:179], v[44:47]
	v_mfma_f32_16x16x32_bf16 v[32:35], v[136:139], v[184:187], v[32:35]
	v_mfma_f32_16x16x32_bf16 v[28:31], v[144:147], v[184:187], v[28:31]
	v_mfma_f32_16x16x32_bf16 v[16:19], v[136:139], v[216:219], v[16:19]
	v_mfma_f32_16x16x32_bf16 v[12:15], v[144:147], v[216:219], v[12:15]
	v_mfma_f32_16x16x32_bf16 v[56:59], v[148:151], v[164:167], v[56:59]
	v_mfma_f32_16x16x32_bf16 v[52:55], v[156:159], v[164:167], v[52:55]
	v_mfma_f32_16x16x32_bf16 v[40:43], v[148:151], v[172:175], v[40:43]
	v_mfma_f32_16x16x32_bf16 v[36:39], v[156:159], v[172:175], v[36:39]
	v_mfma_f32_16x16x32_bf16 v[24:27], v[148:151], v[180:183], v[24:27]
	v_mfma_f32_16x16x32_bf16 v[20:23], v[156:159], v[180:183], v[20:23]
	v_mfma_f32_16x16x32_bf16 v[8:11], v[148:151], v[212:215], v[8:11]
	v_mfma_f32_16x16x32_bf16 v[2:5], v[156:159], v[212:215], v[4:7]
	v_mfma_f32_16x16x32_bf16 v[56:59], v[152:155], v[168:171], v[56:59]
	v_mfma_f32_16x16x32_bf16 v[52:55], v[160:163], v[168:171], v[52:55]
	v_mfma_f32_16x16x32_bf16 v[40:43], v[152:155], v[176:179], v[40:43]
	v_mfma_f32_16x16x32_bf16 v[36:39], v[160:163], v[176:179], v[36:39]
	v_mfma_f32_16x16x32_bf16 v[24:27], v[152:155], v[184:187], v[24:27]
	v_mfma_f32_16x16x32_bf16 v[20:23], v[160:163], v[184:187], v[20:23]
	v_mfma_f32_16x16x32_bf16 v[8:11], v[152:155], v[216:219], v[8:11]
	v_mfma_f32_16x16x32_bf16 v[2:5], v[160:163], v[216:219], v[2:5]
	s_barrier
	s_add_i32 s88, 0, 0x18000
	v_add_u32_e32 v1, s88, v210
	s_add_i32 s89, 0, 0x1c000
	ds_read_b128 v[132:135], v1
	ds_read_b128 v[136:139], v1 offset:1024
	ds_read_b128 v[140:143], v1 offset:2048
	ds_read_b128 v[144:147], v1 offset:3072
	v_add_u32_e32 v1, s89, v210
	ds_read_b128 v[148:151], v1
	ds_read_b128 v[152:155], v1 offset:1024
	ds_read_b128 v[156:159], v1 offset:2048
	ds_read_b128 v[160:163], v1 offset:3072
	s_add_u32 s64, s64, 0x2000
	s_addc_u32 s65, s65, 0
	s_mov_b32 m0, s57
	ds_read_b128 v[164:167], v211 offset:32768
	ds_read_b128 v[168:171], v211 offset:33792
	ds_read_b128 v[172:175], v211 offset:34816
	ds_read_b128 v[176:179], v211 offset:35840
	ds_read_b128 v[180:183], v211 offset:36864
	ds_read_b128 v[184:187], v211 offset:37888
	ds_read_b128 v[212:215], v211 offset:38912
	ds_read_b128 v[216:219], v211 offset:39936
	global_load_lds_dwordx4 v194, s[64:65]
	s_mov_b32 m0, s59
	s_nop 0
	global_load_lds_dwordx4 v190, s[64:65]
	s_waitcnt vmcnt(8)
	s_waitcnt lgkmcnt(0)
	s_barrier
	s_waitcnt lgkmcnt(0)
	v_mfma_f32_16x16x32_bf16 v[128:131], v[132:135], v[164:167], v[128:131]
	v_mfma_f32_16x16x32_bf16 v[124:127], v[140:143], v[164:167], v[124:127]
	v_mfma_f32_16x16x32_bf16 v[112:115], v[132:135], v[172:175], v[112:115]
	v_mfma_f32_16x16x32_bf16 v[108:111], v[140:143], v[172:175], v[108:111]
	v_mfma_f32_16x16x32_bf16 v[96:99], v[132:135], v[180:183], v[96:99]
	v_mfma_f32_16x16x32_bf16 v[92:95], v[140:143], v[180:183], v[92:95]
	v_mfma_f32_16x16x32_bf16 v[80:83], v[132:135], v[212:215], v[80:83]
	v_mfma_f32_16x16x32_bf16 v[76:79], v[140:143], v[212:215], v[76:79]
	v_mfma_f32_16x16x32_bf16 v[128:131], v[136:139], v[168:171], v[128:131]
	v_mfma_f32_16x16x32_bf16 v[124:127], v[144:147], v[168:171], v[124:127]
	v_mfma_f32_16x16x32_bf16 v[112:115], v[136:139], v[176:179], v[112:115]
	v_mfma_f32_16x16x32_bf16 v[108:111], v[144:147], v[176:179], v[108:111]
	v_mfma_f32_16x16x32_bf16 v[96:99], v[136:139], v[184:187], v[96:99]
	v_mfma_f32_16x16x32_bf16 v[92:95], v[144:147], v[184:187], v[92:95]
	v_mfma_f32_16x16x32_bf16 v[80:83], v[136:139], v[216:219], v[80:83]
	v_mfma_f32_16x16x32_bf16 v[76:79], v[144:147], v[216:219], v[76:79]
	v_mfma_f32_16x16x32_bf16 v[120:123], v[148:151], v[164:167], v[120:123]
	v_mfma_f32_16x16x32_bf16 v[116:119], v[156:159], v[164:167], v[116:119]
	v_mfma_f32_16x16x32_bf16 v[104:107], v[148:151], v[172:175], v[104:107]
	v_mfma_f32_16x16x32_bf16 v[100:103], v[156:159], v[172:175], v[100:103]
	v_mfma_f32_16x16x32_bf16 v[88:91], v[148:151], v[180:183], v[88:91]
	v_mfma_f32_16x16x32_bf16 v[84:87], v[156:159], v[180:183], v[84:87]
	v_mfma_f32_16x16x32_bf16 v[72:75], v[148:151], v[212:215], v[72:75]
	v_mfma_f32_16x16x32_bf16 v[68:71], v[156:159], v[212:215], v[68:71]
	v_mfma_f32_16x16x32_bf16 v[120:123], v[152:155], v[168:171], v[120:123]
	v_mfma_f32_16x16x32_bf16 v[116:119], v[160:163], v[168:171], v[116:119]
	v_mfma_f32_16x16x32_bf16 v[104:107], v[152:155], v[176:179], v[104:107]
	v_mfma_f32_16x16x32_bf16 v[100:103], v[160:163], v[176:179], v[100:103]
	v_mfma_f32_16x16x32_bf16 v[88:91], v[152:155], v[184:187], v[88:91]
	v_mfma_f32_16x16x32_bf16 v[84:87], v[160:163], v[184:187], v[84:87]
	v_mfma_f32_16x16x32_bf16 v[72:75], v[152:155], v[216:219], v[72:75]
	v_mfma_f32_16x16x32_bf16 v[68:71], v[160:163], v[216:219], v[68:71]
	s_barrier
	s_add_u32 s98, s50, s10
	s_addc_u32 s99, s51, s11
	s_add_i32 s64, s88, s34
	s_mov_b32 m0, s64
	ds_read_b128 v[164:167], v211 offset:49152
	ds_read_b128 v[168:171], v211 offset:50176
	ds_read_b128 v[172:175], v211 offset:51200
	ds_read_b128 v[176:179], v211 offset:52224
	ds_read_b128 v[180:183], v211 offset:53248
	ds_read_b128 v[184:187], v211 offset:54272
	ds_read_b128 v[212:215], v211 offset:55296
	ds_read_b128 v[216:219], v211 offset:56320
	global_load_lds_dwordx4 v192, s[98:99]
	s_add_i32 m0, s64, 0x2000
	s_add_u32 s50, s50, 0x80080
	v_lshl_add_u64 v[6:7], v[222:223], 0, s[10:11]
	s_addc_u32 s51, s51, 0
	s_add_i32 s64, s89, s34
	global_load_lds_dwordx4 v[6:7], off
	s_mov_b32 m0, s64
	s_nop 0
	global_load_lds_dwordx4 v192, s[50:51]
	s_add_i32 m0, s64, 0x2000
	s_nop 0
	global_load_lds_dwordx4 v188, s[50:51]
	s_mov_b32 m0, s74
	s_nop 0
	global_load_lds_dwordx4 v194, s[48:49]
	s_mov_b32 m0, s75
	s_nop 0
	global_load_lds_dwordx4 v190, s[48:49]
	s_waitcnt vmcnt(8)
	s_waitcnt lgkmcnt(0)
	s_barrier
	s_waitcnt lgkmcnt(0)
	v_mfma_f32_16x16x32_bf16 v[64:67], v[132:135], v[164:167], v[64:67]
	v_mfma_f32_16x16x32_bf16 v[60:63], v[140:143], v[164:167], v[60:63]
	v_mfma_f32_16x16x32_bf16 v[48:51], v[132:135], v[172:175], v[48:51]
	v_mfma_f32_16x16x32_bf16 v[44:47], v[140:143], v[172:175], v[44:47]
	v_mfma_f32_16x16x32_bf16 v[32:35], v[132:135], v[180:183], v[32:35]
	v_mfma_f32_16x16x32_bf16 v[28:31], v[140:143], v[180:183], v[28:31]
	v_mfma_f32_16x16x32_bf16 v[16:19], v[132:135], v[212:215], v[16:19]
	v_mfma_f32_16x16x32_bf16 v[12:15], v[140:143], v[212:215], v[12:15]
	v_mfma_f32_16x16x32_bf16 v[64:67], v[136:139], v[168:171], v[64:67]
	v_mfma_f32_16x16x32_bf16 v[60:63], v[144:147], v[168:171], v[60:63]
	v_mfma_f32_16x16x32_bf16 v[48:51], v[136:139], v[176:179], v[48:51]
	v_mfma_f32_16x16x32_bf16 v[44:47], v[144:147], v[176:179], v[44:47]
	v_mfma_f32_16x16x32_bf16 v[32:35], v[136:139], v[184:187], v[32:35]
	v_mfma_f32_16x16x32_bf16 v[28:31], v[144:147], v[184:187], v[28:31]
	v_mfma_f32_16x16x32_bf16 v[16:19], v[136:139], v[216:219], v[16:19]
	v_mfma_f32_16x16x32_bf16 v[12:15], v[144:147], v[216:219], v[12:15]
	v_mfma_f32_16x16x32_bf16 v[56:59], v[148:151], v[164:167], v[56:59]
	v_mfma_f32_16x16x32_bf16 v[52:55], v[156:159], v[164:167], v[52:55]
	v_mfma_f32_16x16x32_bf16 v[40:43], v[148:151], v[172:175], v[40:43]
	v_mfma_f32_16x16x32_bf16 v[36:39], v[156:159], v[172:175], v[36:39]
	v_mfma_f32_16x16x32_bf16 v[24:27], v[148:151], v[180:183], v[24:27]
	v_mfma_f32_16x16x32_bf16 v[20:23], v[156:159], v[180:183], v[20:23]
	v_mfma_f32_16x16x32_bf16 v[6:9], v[148:151], v[212:215], v[8:11]
	v_mfma_f32_16x16x32_bf16 v[2:5], v[156:159], v[212:215], v[2:5]
	v_mfma_f32_16x16x32_bf16 v[56:59], v[152:155], v[168:171], v[56:59]
	v_mfma_f32_16x16x32_bf16 v[52:55], v[160:163], v[168:171], v[52:55]
	v_mfma_f32_16x16x32_bf16 v[40:43], v[152:155], v[176:179], v[40:43]
	v_mfma_f32_16x16x32_bf16 v[36:39], v[160:163], v[176:179], v[36:39]
	v_mfma_f32_16x16x32_bf16 v[24:27], v[152:155], v[184:187], v[24:27]
	v_mfma_f32_16x16x32_bf16 v[20:23], v[160:163], v[184:187], v[20:23]
	v_mfma_f32_16x16x32_bf16 v[8:11], v[152:155], v[216:219], v[6:9]
	v_mfma_f32_16x16x32_bf16 v[4:7], v[160:163], v[216:219], v[2:5]
	s_barrier
	s_add_i32 s87, s87, 2
	s_add_u32 s41, s41, 0x100
	s_addc_u32 s86, s86, 0
	s_add_u32 s46, s46, 0x10000
	s_addc_u32 s47, s47, 0
	s_cmp_gt_u32 s87, 29
	s_cbranch_scc1 .LBB0_440

.LBB0_507:
	ds_read_b128 v[128:131], v229
	ds_read_b128 v[132:135], v229 offset:1024
	ds_read_b128 v[136:139], v229 offset:2048
	ds_read_b128 v[140:143], v229 offset:3072
	ds_read_b128 v[144:147], v230
	ds_read_b128 v[148:151], v230 offset:1024
	ds_read_b128 v[152:155], v230 offset:2048
	ds_read_b128 v[156:159], v230 offset:3072
	s_add_u32 s44, s42, 0x10000
	s_addc_u32 s45, s43, 0
	s_cmp_eq_u32 s83, 12
	s_cselect_b32 s50, s21, s44
	s_cselect_b32 s51, s8, s45
	s_cselect_b32 s48, s29, s80
	s_cselect_b32 s49, s27, s81
	s_add_u32 s46, s50, 0x8000
	s_addc_u32 s47, s51, 0
	s_add_i32 m0, s23, 0xc000
	ds_read_b128 v[160:163], v231
	ds_read_b128 v[164:167], v231 offset:1024
	ds_read_b128 v[168:171], v231 offset:2048
	ds_read_b128 v[172:175], v231 offset:3072
	ds_read_b128 v[176:179], v231 offset:4096
	ds_read_b128 v[180:183], v231 offset:5120
	ds_read_b128 v[184:187], v231 offset:6144
	ds_read_b128 v[188:191], v231 offset:7168
	global_load_lds_dwordx4 v200, s[42:43]
	s_add_i32 m0, s23, 0xe000
	s_nop 0
	global_load_lds_dwordx4 v202, s[42:43]
	s_waitcnt vmcnt(8)
	s_waitcnt lgkmcnt(0)
	s_barrier
	s_waitcnt lgkmcnt(0)
	v_mfma_f32_16x16x32_bf16 v[124:127], v[128:131], v[160:163], v[124:127]
	v_mfma_f32_16x16x32_bf16 v[120:123], v[136:139], v[160:163], v[120:123]
	v_mfma_f32_16x16x32_bf16 v[108:111], v[128:131], v[168:171], v[108:111]
	v_mfma_f32_16x16x32_bf16 v[104:107], v[136:139], v[168:171], v[104:107]
	v_mfma_f32_16x16x32_bf16 v[92:95], v[128:131], v[176:179], v[92:95]
	v_mfma_f32_16x16x32_bf16 v[88:91], v[136:139], v[176:179], v[88:91]
	v_mfma_f32_16x16x32_bf16 v[76:79], v[128:131], v[184:187], v[76:79]
	v_mfma_f32_16x16x32_bf16 v[72:75], v[136:139], v[184:187], v[72:75]
	v_mfma_f32_16x16x32_bf16 v[124:127], v[132:135], v[164:167], v[124:127]
	v_mfma_f32_16x16x32_bf16 v[120:123], v[140:143], v[164:167], v[120:123]
	v_mfma_f32_16x16x32_bf16 v[108:111], v[132:135], v[172:175], v[108:111]
	v_mfma_f32_16x16x32_bf16 v[104:107], v[140:143], v[172:175], v[104:107]
	v_mfma_f32_16x16x32_bf16 v[92:95], v[132:135], v[180:183], v[92:95]
	v_mfma_f32_16x16x32_bf16 v[88:91], v[140:143], v[180:183], v[88:91]
	v_mfma_f32_16x16x32_bf16 v[76:79], v[132:135], v[188:191], v[76:79]
	v_mfma_f32_16x16x32_bf16 v[72:75], v[140:143], v[188:191], v[72:75]
	v_mfma_f32_16x16x32_bf16 v[116:119], v[144:147], v[160:163], v[116:119]
	v_mfma_f32_16x16x32_bf16 v[112:115], v[152:155], v[160:163], v[112:115]
	v_mfma_f32_16x16x32_bf16 v[100:103], v[144:147], v[168:171], v[100:103]
	v_mfma_f32_16x16x32_bf16 v[96:99], v[152:155], v[168:171], v[96:99]
	v_mfma_f32_16x16x32_bf16 v[84:87], v[144:147], v[176:179], v[84:87]
	v_mfma_f32_16x16x32_bf16 v[80:83], v[152:155], v[176:179], v[80:83]
	v_mfma_f32_16x16x32_bf16 v[68:71], v[144:147], v[184:187], v[68:71]
	v_mfma_f32_16x16x32_bf16 v[64:67], v[152:155], v[184:187], v[64:67]
	v_mfma_f32_16x16x32_bf16 v[116:119], v[148:151], v[164:167], v[116:119]
	v_mfma_f32_16x16x32_bf16 v[112:115], v[156:159], v[164:167], v[112:115]
	v_mfma_f32_16x16x32_bf16 v[100:103], v[148:151], v[172:175], v[100:103]
	v_mfma_f32_16x16x32_bf16 v[96:99], v[156:159], v[172:175], v[96:99]
	v_mfma_f32_16x16x32_bf16 v[84:87], v[148:151], v[180:183], v[84:87]
	v_mfma_f32_16x16x32_bf16 v[80:83], v[156:159], v[180:183], v[80:83]
	v_mfma_f32_16x16x32_bf16 v[68:71], v[148:151], v[188:191], v[68:71]
	v_mfma_f32_16x16x32_bf16 v[64:67], v[156:159], v[188:191], v[64:67]
	s_barrier
	s_add_i32 s42, s77, s35
	s_mov_b32 m0, s42
	ds_read_b128 v[160:163], v231 offset:16384
	ds_read_b128 v[164:167], v231 offset:17408
	ds_read_b128 v[168:171], v231 offset:18432
	ds_read_b128 v[172:175], v231 offset:19456
	ds_read_b128 v[176:179], v231 offset:20480
	ds_read_b128 v[180:183], v231 offset:21504
	ds_read_b128 v[184:187], v231 offset:22528
	ds_read_b128 v[188:191], v231 offset:23552
	global_load_lds_dwordx4 v194, s[48:49]
	s_add_i32 m0, s42, 0x2000
	s_add_u32 s42, s48, 0x40000
	s_addc_u32 s43, s49, 0
	s_add_i32 s84, s78, s35
	global_load_lds_dwordx4 v198, s[48:49]
	s_mov_b32 m0, s84
	s_nop 0
	global_load_lds_dwordx4 v194, s[42:43]
	s_add_i32 m0, s84, 0x2000
	s_nop 0
	global_load_lds_dwordx4 v198, s[42:43]
	s_mov_b32 m0, s23
	s_nop 0
	global_load_lds_dwordx4 v192, s[50:51]
	s_mov_b32 m0, s56
	s_nop 0
	global_load_lds_dwordx4 v196, s[50:51]
	s_waitcnt vmcnt(8)
	s_waitcnt lgkmcnt(0)
	s_barrier
	s_waitcnt lgkmcnt(0)
	v_mfma_f32_16x16x32_bf16 v[60:63], v[128:131], v[160:163], v[60:63]
	v_mfma_f32_16x16x32_bf16 v[56:59], v[136:139], v[160:163], v[56:59]
	v_mfma_f32_16x16x32_bf16 v[44:47], v[128:131], v[168:171], v[44:47]
	v_mfma_f32_16x16x32_bf16 v[40:43], v[136:139], v[168:171], v[40:43]
	v_mfma_f32_16x16x32_bf16 v[28:31], v[128:131], v[176:179], v[28:31]
	v_mfma_f32_16x16x32_bf16 v[24:27], v[136:139], v[176:179], v[24:27]
	v_mfma_f32_16x16x32_bf16 v[12:15], v[128:131], v[184:187], v[12:15]
	v_mfma_f32_16x16x32_bf16 v[8:11], v[136:139], v[184:187], v[8:11]
	v_mfma_f32_16x16x32_bf16 v[60:63], v[132:135], v[164:167], v[60:63]
	v_mfma_f32_16x16x32_bf16 v[56:59], v[140:143], v[164:167], v[56:59]
	v_mfma_f32_16x16x32_bf16 v[44:47], v[132:135], v[172:175], v[44:47]
	v_mfma_f32_16x16x32_bf16 v[40:43], v[140:143], v[172:175], v[40:43]
	v_mfma_f32_16x16x32_bf16 v[28:31], v[132:135], v[180:183], v[28:31]
	v_mfma_f32_16x16x32_bf16 v[24:27], v[140:143], v[180:183], v[24:27]
	v_mfma_f32_16x16x32_bf16 v[12:15], v[132:135], v[188:191], v[12:15]
	v_mfma_f32_16x16x32_bf16 v[8:11], v[140:143], v[188:191], v[8:11]
	v_mfma_f32_16x16x32_bf16 v[52:55], v[144:147], v[160:163], v[52:55]
	v_mfma_f32_16x16x32_bf16 v[48:51], v[152:155], v[160:163], v[48:51]
	v_mfma_f32_16x16x32_bf16 v[36:39], v[144:147], v[168:171], v[36:39]
	v_mfma_f32_16x16x32_bf16 v[32:35], v[152:155], v[168:171], v[32:35]
	v_mfma_f32_16x16x32_bf16 v[20:23], v[144:147], v[176:179], v[20:23]
	v_mfma_f32_16x16x32_bf16 v[16:19], v[152:155], v[176:179], v[16:19]
	v_mfma_f32_16x16x32_bf16 v[4:7], v[144:147], v[184:187], v[4:7]
	v_mfma_f32_16x16x32_bf16 v[0:3], v[152:155], v[184:187], v[0:3]
	v_mfma_f32_16x16x32_bf16 v[52:55], v[148:151], v[164:167], v[52:55]
	v_mfma_f32_16x16x32_bf16 v[48:51], v[156:159], v[164:167], v[48:51]
	v_mfma_f32_16x16x32_bf16 v[36:39], v[148:151], v[172:175], v[36:39]
	v_mfma_f32_16x16x32_bf16 v[32:35], v[156:159], v[172:175], v[32:35]
	v_mfma_f32_16x16x32_bf16 v[20:23], v[148:151], v[180:183], v[20:23]
	v_mfma_f32_16x16x32_bf16 v[16:19], v[156:159], v[180:183], v[16:19]
	v_mfma_f32_16x16x32_bf16 v[4:7], v[148:151], v[188:191], v[4:7]
	v_mfma_f32_16x16x32_bf16 v[0:3], v[156:159], v[188:191], v[0:3]
	s_barrier
	s_add_i32 s84, 0, 0x18000
	s_add_i32 s85, 0, 0x1c000
	v_add_u32_e32 v140, s84, v228
	v_add_u32_e32 v156, s85, v228
	ds_read_b128 v[128:131], v140
	ds_read_b128 v[132:135], v140 offset:1024
	ds_read_b128 v[136:139], v140 offset:2048
	ds_read_b128 v[140:143], v140 offset:3072
	ds_read_b128 v[144:147], v156
	ds_read_b128 v[148:151], v156 offset:1024
	ds_read_b128 v[152:155], v156 offset:2048
	ds_read_b128 v[156:159], v156 offset:3072
	s_add_u32 s42, s50, 0x2000
	s_addc_u32 s43, s51, 0
	s_mov_b32 m0, s57
	ds_read_b128 v[160:163], v231 offset:32768
	ds_read_b128 v[164:167], v231 offset:33792
	ds_read_b128 v[168:171], v231 offset:34816
	ds_read_b128 v[172:175], v231 offset:35840
	ds_read_b128 v[176:179], v231 offset:36864
	ds_read_b128 v[180:183], v231 offset:37888
	ds_read_b128 v[184:187], v231 offset:38912
	ds_read_b128 v[188:191], v231 offset:39936
	global_load_lds_dwordx4 v192, s[42:43]
	s_mov_b32 m0, s59
	s_nop 0
	global_load_lds_dwordx4 v196, s[42:43]
	s_waitcnt vmcnt(8)
	s_waitcnt lgkmcnt(0)
	s_barrier
	s_waitcnt lgkmcnt(0)
	v_mfma_f32_16x16x32_bf16 v[124:127], v[128:131], v[160:163], v[124:127]
	v_mfma_f32_16x16x32_bf16 v[120:123], v[136:139], v[160:163], v[120:123]
	v_mfma_f32_16x16x32_bf16 v[108:111], v[128:131], v[168:171], v[108:111]
	v_mfma_f32_16x16x32_bf16 v[104:107], v[136:139], v[168:171], v[104:107]
	v_mfma_f32_16x16x32_bf16 v[92:95], v[128:131], v[176:179], v[92:95]
	v_mfma_f32_16x16x32_bf16 v[88:91], v[136:139], v[176:179], v[88:91]
	v_mfma_f32_16x16x32_bf16 v[76:79], v[128:131], v[184:187], v[76:79]
	v_mfma_f32_16x16x32_bf16 v[72:75], v[136:139], v[184:187], v[72:75]
	v_mfma_f32_16x16x32_bf16 v[124:127], v[132:135], v[164:167], v[124:127]
	v_mfma_f32_16x16x32_bf16 v[120:123], v[140:143], v[164:167], v[120:123]
	v_mfma_f32_16x16x32_bf16 v[108:111], v[132:135], v[172:175], v[108:111]
	v_mfma_f32_16x16x32_bf16 v[104:107], v[140:143], v[172:175], v[104:107]
	v_mfma_f32_16x16x32_bf16 v[92:95], v[132:135], v[180:183], v[92:95]
	v_mfma_f32_16x16x32_bf16 v[88:91], v[140:143], v[180:183], v[88:91]
	v_mfma_f32_16x16x32_bf16 v[76:79], v[132:135], v[188:191], v[76:79]
	v_mfma_f32_16x16x32_bf16 v[72:75], v[140:143], v[188:191], v[72:75]
	v_mfma_f32_16x16x32_bf16 v[116:119], v[144:147], v[160:163], v[116:119]
	v_mfma_f32_16x16x32_bf16 v[112:115], v[152:155], v[160:163], v[112:115]
	v_mfma_f32_16x16x32_bf16 v[100:103], v[144:147], v[168:171], v[100:103]
	v_mfma_f32_16x16x32_bf16 v[96:99], v[152:155], v[168:171], v[96:99]
	v_mfma_f32_16x16x32_bf16 v[84:87], v[144:147], v[176:179], v[84:87]
	v_mfma_f32_16x16x32_bf16 v[80:83], v[152:155], v[176:179], v[80:83]
	v_mfma_f32_16x16x32_bf16 v[68:71], v[144:147], v[184:187], v[68:71]
	v_mfma_f32_16x16x32_bf16 v[64:67], v[152:155], v[184:187], v[64:67]
	v_mfma_f32_16x16x32_bf16 v[116:119], v[148:151], v[164:167], v[116:119]
	v_mfma_f32_16x16x32_bf16 v[112:115], v[156:159], v[164:167], v[112:115]
	v_mfma_f32_16x16x32_bf16 v[100:103], v[148:151], v[172:175], v[100:103]
	v_mfma_f32_16x16x32_bf16 v[96:99], v[156:159], v[172:175], v[96:99]
	v_mfma_f32_16x16x32_bf16 v[84:87], v[148:151], v[180:183], v[84:87]
	v_mfma_f32_16x16x32_bf16 v[80:83], v[156:159], v[180:183], v[80:83]
	v_mfma_f32_16x16x32_bf16 v[68:71], v[148:151], v[188:191], v[68:71]
	v_mfma_f32_16x16x32_bf16 v[64:67], v[156:159], v[188:191], v[64:67]
	s_barrier
	s_add_u32 s98, s48, s16
	s_addc_u32 s99, s49, s17
	s_add_i32 s42, s84, s35
	s_mov_b32 m0, s42
	ds_read_b128 v[160:163], v231 offset:49152
	ds_read_b128 v[164:167], v231 offset:50176
	ds_read_b128 v[168:171], v231 offset:51200
	ds_read_b128 v[172:175], v231 offset:52224
	ds_read_b128 v[176:179], v231 offset:53248
	ds_read_b128 v[180:183], v231 offset:54272
	ds_read_b128 v[184:187], v231 offset:55296
	ds_read_b128 v[188:191], v231 offset:56320
	global_load_lds_dwordx4 v194, s[98:99]
	s_add_i32 m0, s42, 0x2000
	s_add_u32 s42, s48, 0x40080
	s_addc_u32 s43, s49, 0
	s_add_i32 s48, s85, s35
	global_load_lds_dwordx4 v198, s[98:99]
	s_mov_b32 m0, s48
	s_nop 0
	global_load_lds_dwordx4 v194, s[42:43]
	s_add_i32 m0, s48, 0x2000
	s_nop 0
	global_load_lds_dwordx4 v198, s[42:43]
	s_mov_b32 m0, s75
	s_nop 0
	global_load_lds_dwordx4 v192, s[46:47]
	s_mov_b32 m0, s76
	s_nop 0
	global_load_lds_dwordx4 v196, s[46:47]
	s_waitcnt vmcnt(8)
	s_waitcnt lgkmcnt(0)
	s_barrier
	s_waitcnt lgkmcnt(0)
	v_mfma_f32_16x16x32_bf16 v[60:63], v[128:131], v[160:163], v[60:63]
	v_mfma_f32_16x16x32_bf16 v[56:59], v[136:139], v[160:163], v[56:59]
	v_mfma_f32_16x16x32_bf16 v[44:47], v[128:131], v[168:171], v[44:47]
	v_mfma_f32_16x16x32_bf16 v[40:43], v[136:139], v[168:171], v[40:43]
	v_mfma_f32_16x16x32_bf16 v[28:31], v[128:131], v[176:179], v[28:31]
	v_mfma_f32_16x16x32_bf16 v[24:27], v[136:139], v[176:179], v[24:27]
	v_mfma_f32_16x16x32_bf16 v[12:15], v[128:131], v[184:187], v[12:15]
	v_mfma_f32_16x16x32_bf16 v[8:11], v[136:139], v[184:187], v[8:11]
	v_mfma_f32_16x16x32_bf16 v[60:63], v[132:135], v[164:167], v[60:63]
	v_mfma_f32_16x16x32_bf16 v[56:59], v[140:143], v[164:167], v[56:59]
	v_mfma_f32_16x16x32_bf16 v[44:47], v[132:135], v[172:175], v[44:47]
	v_mfma_f32_16x16x32_bf16 v[40:43], v[140:143], v[172:175], v[40:43]
	v_mfma_f32_16x16x32_bf16 v[28:31], v[132:135], v[180:183], v[28:31]
	v_mfma_f32_16x16x32_bf16 v[24:27], v[140:143], v[180:183], v[24:27]
	v_mfma_f32_16x16x32_bf16 v[12:15], v[132:135], v[188:191], v[12:15]
	v_mfma_f32_16x16x32_bf16 v[8:11], v[140:143], v[188:191], v[8:11]
	v_mfma_f32_16x16x32_bf16 v[52:55], v[144:147], v[160:163], v[52:55]
	v_mfma_f32_16x16x32_bf16 v[48:51], v[152:155], v[160:163], v[48:51]
	v_mfma_f32_16x16x32_bf16 v[36:39], v[144:147], v[168:171], v[36:39]
	v_mfma_f32_16x16x32_bf16 v[32:35], v[152:155], v[168:171], v[32:35]
	v_mfma_f32_16x16x32_bf16 v[20:23], v[144:147], v[176:179], v[20:23]
	v_mfma_f32_16x16x32_bf16 v[16:19], v[152:155], v[176:179], v[16:19]
	v_mfma_f32_16x16x32_bf16 v[4:7], v[144:147], v[184:187], v[4:7]
	v_mfma_f32_16x16x32_bf16 v[0:3], v[152:155], v[184:187], v[0:3]
	v_mfma_f32_16x16x32_bf16 v[52:55], v[148:151], v[164:167], v[52:55]
	v_mfma_f32_16x16x32_bf16 v[48:51], v[156:159], v[164:167], v[48:51]
	v_mfma_f32_16x16x32_bf16 v[36:39], v[148:151], v[172:175], v[36:39]
	v_mfma_f32_16x16x32_bf16 v[32:35], v[156:159], v[172:175], v[32:35]
	v_mfma_f32_16x16x32_bf16 v[20:23], v[148:151], v[180:183], v[20:23]
	v_mfma_f32_16x16x32_bf16 v[16:19], v[156:159], v[180:183], v[16:19]
	v_mfma_f32_16x16x32_bf16 v[4:7], v[148:151], v[188:191], v[4:7]
	v_mfma_f32_16x16x32_bf16 v[0:3], v[156:159], v[188:191], v[0:3]
	s_barrier
	s_add_i32 s83, s83, 2
	s_add_u32 s80, s80, 0x100
	s_addc_u32 s81, s81, 0
	s_cmp_gt_u32 s83, 13
	s_mov_b64 s[42:43], s[44:45]
	s_cbranch_scc0 .LBB0_507
	v_mov_b32_e32 v233, v227
	v_mov_b32_e32 v144, v226
	s_lshl_b32 s8, s22, 8
	s_or_b32 s8, s8, s73
	v_lshlrev_b32_e32 v208, 3, v233
	v_add_u32_e32 v128, s8, v208
	s_lshr_b32 s8, s20, 4
	s_mul_i32 s42, s8, 0x1800
	s_ashr_i32 s43, s42, 31
	s_lshl_b64 s[42:43], s[42:43], 2
	s_add_u32 s42, s69, s42
	v_ashrrev_i32_e32 v129, 31, v128
	v_add_u32_e32 v210, s72, v144
	s_addc_u32 s43, s70, s43
	v_lshlrev_b64 v[212:213], 2, v[128:129]
	v_lshl_add_u32 v216, s20, 8, v210
	v_lshl_add_u64 v[214:215], s[42:43], 0, v[212:213]
	v_ashrrev_i32_e32 v217, 31, v216
	v_add_co_u32_e32 v128, vcc, s65, v214
	v_lshl_add_u64 v[218:219], s[36:37], 0, v[212:213]
	v_lshlrev_b64 v[144:145], 12, v[216:217]
	v_add_u32_e32 v224, 16, v216
	v_lshl_add_u64 v[132:133], v[214:215], 0, s[10:11]
	v_addc_co_u32_e32 v129, vcc, 0, v215, vcc
	v_lshl_add_u64 v[144:145], v[218:219], 0, v[144:145]
	v_ashrrev_i32_e32 v225, 31, v224
	global_load_dwordx4 v[140:143], v[128:129], off nt
	s_nop 0
	global_load_dwordx4 v[128:131], v[132:133], off offset:528 nt
	global_load_dwordx4 v[136:139], v[132:133], off offset:16 nt
	s_nop 0
	global_load_dwordx4 v[132:135], v[132:133], off offset:512 nt
	s_nop 0
	global_load_dwordx4 v[234:237], v[144:145], off offset:16 nt
	global_load_dwordx4 v[238:241], v[144:145], off nt
	global_load_dwordx4 v[242:245], v[144:145], off offset:528 nt
	global_load_dwordx4 v[246:249], v[144:145], off offset:512 nt
	v_lshlrev_b64 v[144:145], 12, v[224:225]
	v_add_u32_e32 v222, 32, v216
	v_lshl_add_u64 v[144:145], v[218:219], 0, v[144:145]
	v_ashrrev_i32_e32 v223, 31, v222
	global_load_dwordx4 v[184:187], v[144:145], off offset:16 nt
	global_load_dwordx4 v[188:191], v[144:145], off nt
	global_load_dwordx4 v[176:179], v[144:145], off offset:528 nt
	global_load_dwordx4 v[180:183], v[144:145], off offset:512 nt
	v_lshlrev_b64 v[144:145], 12, v[222:223]
	v_add_u32_e32 v220, 48, v216
	v_lshl_add_u64 v[144:145], v[218:219], 0, v[144:145]
	v_ashrrev_i32_e32 v221, 31, v220
	global_load_dwordx4 v[168:171], v[144:145], off offset:16 nt
	global_load_dwordx4 v[172:175], v[144:145], off nt
	global_load_dwordx4 v[160:163], v[144:145], off offset:528 nt
	global_load_dwordx4 v[164:167], v[144:145], off offset:512 nt
	v_lshlrev_b64 v[144:145], 12, v[220:221]
	v_lshl_add_u64 v[148:149], v[218:219], 0, v[144:145]
	global_load_dwordx4 v[152:155], v[148:149], off offset:16 nt
	global_load_dwordx4 v[156:159], v[148:149], off nt
	global_load_dwordx4 v[144:147], v[148:149], off offset:528 nt
	s_nop 0
	global_load_dwordx4 v[148:151], v[148:149], off offset:512 nt
	v_and_b32_e32 v211, 64, v232
	v_xor_b32_e32 v209, 16, v232
	v_add_u32_e32 v211, 64, v211
	v_cmp_lt_i32_e32 vcc, v209, v211
	v_xor_b32_e32 v250, 32, v232
	s_lshl_b32 s42, s22, 2
	v_cndmask_b32_e32 v209, v232, v209, vcc
	v_cmp_lt_i32_e32 vcc, v250, v211
	v_lshlrev_b32_e32 v209, 2, v209
	s_ashr_i32 s43, s42, 31
	v_cndmask_b32_e32 v211, v232, v250, vcc
	v_lshlrev_b32_e32 v211, 2, v211
	v_cmp_eq_u32_e32 vcc, 0, v233
	s_waitcnt vmcnt(0)
	v_pk_fma_f32 v[126:127], v[126:127], v[142:143], v[240:241]
	v_pk_fma_f32 v[124:125], v[124:125], v[140:141], v[238:239]
	v_pk_fma_f32 v[120:121], v[120:121], v[136:137], v[234:235]
	v_mul_f32_e32 v233, v125, v125
	v_mul_f32_e32 v234, v127, v127
	v_fmac_f32_e32 v233, v124, v124
	v_fmac_f32_e32 v234, v126, v126
	v_add_f32_e32 v233, v233, v234
	v_mul_f32_e32 v234, v121, v121
	v_pk_fma_f32 v[122:123], v[122:123], v[138:139], v[236:237]
	v_fmac_f32_e32 v234, v120, v120
	v_add_f32_e32 v233, v233, v234
	v_mul_f32_e32 v234, v123, v123
	v_fmac_f32_e32 v234, v122, v122
	v_pk_fma_f32 v[118:119], v[118:119], v[134:135], v[248:249]
	v_pk_fma_f32 v[116:117], v[116:117], v[132:133], v[246:247]
	v_add_f32_e32 v233, v234, v233
	v_mul_f32_e32 v234, v117, v117
	v_mul_f32_e32 v235, v119, v119
	v_pk_fma_f32 v[112:113], v[112:113], v[128:129], v[242:243]
	v_fmac_f32_e32 v234, v116, v116
	v_fmac_f32_e32 v235, v118, v118
	v_add_f32_e32 v234, v234, v235
	v_mul_f32_e32 v235, v113, v113
	v_pk_fma_f32 v[114:115], v[114:115], v[130:131], v[244:245]
	v_fmac_f32_e32 v235, v112, v112
	v_add_f32_e32 v234, v234, v235
	v_mul_f32_e32 v235, v115, v115
	v_fmac_f32_e32 v235, v114, v114
	v_add_f32_e32 v234, v235, v234
	v_add_f32_e32 v233, v233, v234
	ds_bpermute_b32 v234, v209, v233
	s_waitcnt lgkmcnt(0)
	v_add_f32_e32 v233, v233, v234
	ds_bpermute_b32 v234, v211, v233
	s_and_saveexec_b64 s[44:45], vcc
	s_cbranch_execz .LBB0_510
	v_lshlrev_b64 v[236:237], 6, v[216:217]
	v_lshl_add_u64 v[236:237], s[12:13], 0, v[236:237]
	v_lshl_add_u64 v[236:237], s[42:43], 2, v[236:237]
	s_lshl_b32 s8, s71, 2
	v_lshl_add_u64 v[236:237], v[236:237], 0, s[8:9]
	s_waitcnt lgkmcnt(0)
	v_add_f32_e32 v217, v233, v234
	global_store_dword v[236:237], v217, off

.LBB0_568:
	ds_read_b128 v[128:131], v167
	ds_read_b128 v[132:135], v167 offset:1024
	ds_read_b128 v[136:139], v167 offset:2048
	ds_read_b128 v[140:143], v167 offset:3072
	ds_read_b128 v[160:163], v168
	ds_read_b128 v[170:173], v168 offset:1024
	ds_read_b128 v[174:177], v168 offset:2048
	ds_read_b128 v[178:181], v168 offset:3072
	s_add_u32 s36, s28, 0x10000
	s_addc_u32 s37, s29, 0
	s_cmp_eq_u32 s76, 12
	s_cselect_b32 s42, s27, s36
	s_cselect_b32 s43, s19, s37
	s_cselect_b32 s40, s73, s74
	s_cselect_b32 s41, s17, s75
	s_add_u32 s38, s42, 0x8000
	s_addc_u32 s39, s43, 0
	s_add_i32 m0, s44, 0xc000
	ds_read_b128 v[182:185], v169
	ds_read_b128 v[186:189], v169 offset:1024
	ds_read_b128 v[190:193], v169 offset:2048
	ds_read_b128 v[194:197], v169 offset:3072
	ds_read_b128 v[198:201], v169 offset:4096
	ds_read_b128 v[202:205], v169 offset:5120
	ds_read_b128 v[206:209], v169 offset:6144
	ds_read_b128 v[210:213], v169 offset:7168
	global_load_lds_dwordx4 v152, s[28:29]
	s_add_i32 m0, s44, 0xe000
	s_nop 0
	global_load_lds_dwordx4 v154, s[28:29]
	s_waitcnt vmcnt(8)
	s_waitcnt lgkmcnt(0)
	s_barrier
	s_waitcnt lgkmcnt(0)
	v_mfma_f32_16x16x32_bf16 v[124:127], v[128:131], v[182:185], v[124:127]
	v_mfma_f32_16x16x32_bf16 v[120:123], v[136:139], v[182:185], v[120:123]
	v_mfma_f32_16x16x32_bf16 v[116:119], v[128:131], v[190:193], v[116:119]
	v_mfma_f32_16x16x32_bf16 v[112:115], v[136:139], v[190:193], v[112:115]
	v_mfma_f32_16x16x32_bf16 v[92:95], v[128:131], v[198:201], v[92:95]
	v_mfma_f32_16x16x32_bf16 v[88:91], v[136:139], v[198:201], v[88:91]
	v_mfma_f32_16x16x32_bf16 v[76:79], v[128:131], v[206:209], v[76:79]
	v_mfma_f32_16x16x32_bf16 v[72:75], v[136:139], v[206:209], v[72:75]
	v_mfma_f32_16x16x32_bf16 v[124:127], v[132:135], v[186:189], v[124:127]
	v_mfma_f32_16x16x32_bf16 v[120:123], v[140:143], v[186:189], v[120:123]
	v_mfma_f32_16x16x32_bf16 v[116:119], v[132:135], v[194:197], v[116:119]
	v_mfma_f32_16x16x32_bf16 v[112:115], v[140:143], v[194:197], v[112:115]
	v_mfma_f32_16x16x32_bf16 v[92:95], v[132:135], v[202:205], v[92:95]
	v_mfma_f32_16x16x32_bf16 v[88:91], v[140:143], v[202:205], v[88:91]
	v_mfma_f32_16x16x32_bf16 v[76:79], v[132:135], v[210:213], v[76:79]
	v_mfma_f32_16x16x32_bf16 v[72:75], v[140:143], v[210:213], v[72:75]
	v_mfma_f32_16x16x32_bf16 v[108:111], v[160:163], v[182:185], v[108:111]
	v_mfma_f32_16x16x32_bf16 v[104:107], v[174:177], v[182:185], v[104:107]
	v_mfma_f32_16x16x32_bf16 v[100:103], v[160:163], v[190:193], v[100:103]
	v_mfma_f32_16x16x32_bf16 v[96:99], v[174:177], v[190:193], v[96:99]
	v_mfma_f32_16x16x32_bf16 v[84:87], v[160:163], v[198:201], v[84:87]
	v_mfma_f32_16x16x32_bf16 v[80:83], v[174:177], v[198:201], v[80:83]
	v_mfma_f32_16x16x32_bf16 v[68:71], v[160:163], v[206:209], v[68:71]
	v_mfma_f32_16x16x32_bf16 v[64:67], v[174:177], v[206:209], v[64:67]
	v_mfma_f32_16x16x32_bf16 v[108:111], v[170:173], v[186:189], v[108:111]
	v_mfma_f32_16x16x32_bf16 v[104:107], v[178:181], v[186:189], v[104:107]
	v_mfma_f32_16x16x32_bf16 v[100:103], v[170:173], v[194:197], v[100:103]
	v_mfma_f32_16x16x32_bf16 v[96:99], v[178:181], v[194:197], v[96:99]
	v_mfma_f32_16x16x32_bf16 v[84:87], v[170:173], v[202:205], v[84:87]
	v_mfma_f32_16x16x32_bf16 v[80:83], v[178:181], v[202:205], v[80:83]
	v_mfma_f32_16x16x32_bf16 v[68:71], v[170:173], v[210:213], v[68:71]
	v_mfma_f32_16x16x32_bf16 v[64:67], v[178:181], v[210:213], v[64:67]
	s_barrier
	s_add_i32 s28, s70, s35
	s_mov_b32 m0, s28
	ds_read_b128 v[182:185], v169 offset:16384
	ds_read_b128 v[186:189], v169 offset:17408
	ds_read_b128 v[190:193], v169 offset:18432
	ds_read_b128 v[194:197], v169 offset:19456
	ds_read_b128 v[198:201], v169 offset:20480
	ds_read_b128 v[202:205], v169 offset:21504
	ds_read_b128 v[206:209], v169 offset:22528
	ds_read_b128 v[210:213], v169 offset:23552
	global_load_lds_dwordx4 v148, s[40:41]
	s_add_i32 m0, s28, 0x2000
	s_add_u32 s28, s40, 0x40000
	s_addc_u32 s29, s41, 0
	s_add_i32 s77, s71, s35
	global_load_lds_dwordx4 v144, s[40:41]
	s_mov_b32 m0, s77
	s_nop 0
	global_load_lds_dwordx4 v148, s[28:29]
	s_add_i32 m0, s77, 0x2000
	s_nop 0
	global_load_lds_dwordx4 v144, s[28:29]
	s_mov_b32 m0, s44
	s_nop 0
	global_load_lds_dwordx4 v150, s[42:43]
	s_mov_b32 m0, s45
	s_nop 0
	global_load_lds_dwordx4 v146, s[42:43]
	s_waitcnt vmcnt(8)
	s_waitcnt lgkmcnt(0)
	s_barrier
	s_waitcnt lgkmcnt(0)
	v_mfma_f32_16x16x32_bf16 v[60:63], v[128:131], v[182:185], v[60:63]
	v_mfma_f32_16x16x32_bf16 v[56:59], v[136:139], v[182:185], v[56:59]
	v_mfma_f32_16x16x32_bf16 v[44:47], v[128:131], v[190:193], v[44:47]
	v_mfma_f32_16x16x32_bf16 v[40:43], v[136:139], v[190:193], v[40:43]
	v_mfma_f32_16x16x32_bf16 v[28:31], v[128:131], v[198:201], v[28:31]
	v_mfma_f32_16x16x32_bf16 v[24:27], v[136:139], v[198:201], v[24:27]
	v_mfma_f32_16x16x32_bf16 v[12:15], v[128:131], v[206:209], v[12:15]
	v_mfma_f32_16x16x32_bf16 v[8:11], v[136:139], v[206:209], v[8:11]
	v_mfma_f32_16x16x32_bf16 v[60:63], v[132:135], v[186:189], v[60:63]
	v_mfma_f32_16x16x32_bf16 v[56:59], v[140:143], v[186:189], v[56:59]
	v_mfma_f32_16x16x32_bf16 v[44:47], v[132:135], v[194:197], v[44:47]
	v_mfma_f32_16x16x32_bf16 v[40:43], v[140:143], v[194:197], v[40:43]
	v_mfma_f32_16x16x32_bf16 v[28:31], v[132:135], v[202:205], v[28:31]
	v_mfma_f32_16x16x32_bf16 v[24:27], v[140:143], v[202:205], v[24:27]
	v_mfma_f32_16x16x32_bf16 v[12:15], v[132:135], v[210:213], v[12:15]
	v_mfma_f32_16x16x32_bf16 v[8:11], v[140:143], v[210:213], v[8:11]
	v_mfma_f32_16x16x32_bf16 v[52:55], v[160:163], v[182:185], v[52:55]
	v_mfma_f32_16x16x32_bf16 v[48:51], v[174:177], v[182:185], v[48:51]
	v_mfma_f32_16x16x32_bf16 v[36:39], v[160:163], v[190:193], v[36:39]
	v_mfma_f32_16x16x32_bf16 v[32:35], v[174:177], v[190:193], v[32:35]
	v_mfma_f32_16x16x32_bf16 v[20:23], v[160:163], v[198:201], v[20:23]
	v_mfma_f32_16x16x32_bf16 v[16:19], v[174:177], v[198:201], v[16:19]
	v_mfma_f32_16x16x32_bf16 v[4:7], v[160:163], v[206:209], v[4:7]
	v_mfma_f32_16x16x32_bf16 v[0:3], v[174:177], v[206:209], v[0:3]
	v_mfma_f32_16x16x32_bf16 v[52:55], v[170:173], v[186:189], v[52:55]
	v_mfma_f32_16x16x32_bf16 v[48:51], v[178:181], v[186:189], v[48:51]
	v_mfma_f32_16x16x32_bf16 v[36:39], v[170:173], v[194:197], v[36:39]
	v_mfma_f32_16x16x32_bf16 v[32:35], v[178:181], v[194:197], v[32:35]
	v_mfma_f32_16x16x32_bf16 v[20:23], v[170:173], v[202:205], v[20:23]
	v_mfma_f32_16x16x32_bf16 v[16:19], v[178:181], v[202:205], v[16:19]
	v_mfma_f32_16x16x32_bf16 v[4:7], v[170:173], v[210:213], v[4:7]
	v_mfma_f32_16x16x32_bf16 v[0:3], v[178:181], v[210:213], v[0:3]
	s_barrier
	s_add_i32 s77, 0, 0x18000
	s_add_i32 s78, 0, 0x1c000
	v_add_u32_e32 v140, s77, v166
	v_add_u32_e32 v178, s78, v166
	ds_read_b128 v[128:131], v140
	ds_read_b128 v[132:135], v140 offset:1024
	ds_read_b128 v[136:139], v140 offset:2048
	ds_read_b128 v[140:143], v140 offset:3072
	ds_read_b128 v[160:163], v178
	ds_read_b128 v[170:173], v178 offset:1024
	ds_read_b128 v[174:177], v178 offset:2048
	ds_read_b128 v[178:181], v178 offset:3072
	s_add_u32 s28, s42, 0x2000
	s_addc_u32 s29, s43, 0
	s_mov_b32 m0, s46
	ds_read_b128 v[182:185], v169 offset:32768
	ds_read_b128 v[186:189], v169 offset:33792
	ds_read_b128 v[190:193], v169 offset:34816
	ds_read_b128 v[194:197], v169 offset:35840
	ds_read_b128 v[198:201], v169 offset:36864
	ds_read_b128 v[202:205], v169 offset:37888
	ds_read_b128 v[206:209], v169 offset:38912
	ds_read_b128 v[210:213], v169 offset:39936
	global_load_lds_dwordx4 v150, s[28:29]
	s_mov_b32 m0, s47
	s_nop 0
	global_load_lds_dwordx4 v146, s[28:29]
	s_waitcnt vmcnt(8)
	s_waitcnt lgkmcnt(0)
	s_barrier
	s_waitcnt lgkmcnt(0)
	v_mfma_f32_16x16x32_bf16 v[124:127], v[128:131], v[182:185], v[124:127]
	v_mfma_f32_16x16x32_bf16 v[120:123], v[136:139], v[182:185], v[120:123]
	v_mfma_f32_16x16x32_bf16 v[116:119], v[128:131], v[190:193], v[116:119]
	v_mfma_f32_16x16x32_bf16 v[112:115], v[136:139], v[190:193], v[112:115]
	v_mfma_f32_16x16x32_bf16 v[92:95], v[128:131], v[198:201], v[92:95]
	v_mfma_f32_16x16x32_bf16 v[88:91], v[136:139], v[198:201], v[88:91]
	v_mfma_f32_16x16x32_bf16 v[76:79], v[128:131], v[206:209], v[76:79]
	v_mfma_f32_16x16x32_bf16 v[72:75], v[136:139], v[206:209], v[72:75]
	v_mfma_f32_16x16x32_bf16 v[124:127], v[132:135], v[186:189], v[124:127]
	v_mfma_f32_16x16x32_bf16 v[120:123], v[140:143], v[186:189], v[120:123]
	v_mfma_f32_16x16x32_bf16 v[116:119], v[132:135], v[194:197], v[116:119]
	v_mfma_f32_16x16x32_bf16 v[112:115], v[140:143], v[194:197], v[112:115]
	v_mfma_f32_16x16x32_bf16 v[92:95], v[132:135], v[202:205], v[92:95]
	v_mfma_f32_16x16x32_bf16 v[88:91], v[140:143], v[202:205], v[88:91]
	v_mfma_f32_16x16x32_bf16 v[76:79], v[132:135], v[210:213], v[76:79]
	v_mfma_f32_16x16x32_bf16 v[72:75], v[140:143], v[210:213], v[72:75]
	v_mfma_f32_16x16x32_bf16 v[108:111], v[160:163], v[182:185], v[108:111]
	v_mfma_f32_16x16x32_bf16 v[104:107], v[174:177], v[182:185], v[104:107]
	v_mfma_f32_16x16x32_bf16 v[100:103], v[160:163], v[190:193], v[100:103]
	v_mfma_f32_16x16x32_bf16 v[96:99], v[174:177], v[190:193], v[96:99]
	v_mfma_f32_16x16x32_bf16 v[84:87], v[160:163], v[198:201], v[84:87]
	v_mfma_f32_16x16x32_bf16 v[80:83], v[174:177], v[198:201], v[80:83]
	v_mfma_f32_16x16x32_bf16 v[68:71], v[160:163], v[206:209], v[68:71]
	v_mfma_f32_16x16x32_bf16 v[64:67], v[174:177], v[206:209], v[64:67]
	v_mfma_f32_16x16x32_bf16 v[108:111], v[170:173], v[186:189], v[108:111]
	v_mfma_f32_16x16x32_bf16 v[104:107], v[178:181], v[186:189], v[104:107]
	v_mfma_f32_16x16x32_bf16 v[100:103], v[170:173], v[194:197], v[100:103]
	v_mfma_f32_16x16x32_bf16 v[96:99], v[178:181], v[194:197], v[96:99]
	v_mfma_f32_16x16x32_bf16 v[84:87], v[170:173], v[202:205], v[84:87]
	v_mfma_f32_16x16x32_bf16 v[80:83], v[178:181], v[202:205], v[80:83]
	v_mfma_f32_16x16x32_bf16 v[68:71], v[170:173], v[210:213], v[68:71]
	v_mfma_f32_16x16x32_bf16 v[64:67], v[178:181], v[210:213], v[64:67]
	s_barrier
	s_add_u32 s98, s40, s12
	s_addc_u32 s99, s41, s13
	s_add_i32 s28, s77, s35
	s_mov_b32 m0, s28
	ds_read_b128 v[182:185], v169 offset:49152
	ds_read_b128 v[186:189], v169 offset:50176
	ds_read_b128 v[190:193], v169 offset:51200
	ds_read_b128 v[194:197], v169 offset:52224
	ds_read_b128 v[198:201], v169 offset:53248
	ds_read_b128 v[202:205], v169 offset:54272
	ds_read_b128 v[206:209], v169 offset:55296
	ds_read_b128 v[210:213], v169 offset:56320
	global_load_lds_dwordx4 v148, s[98:99]
	s_add_i32 m0, s28, 0x2000
	s_add_u32 s28, s40, 0x40080
	s_addc_u32 s29, s41, 0
	s_add_i32 s40, s78, s35
	global_load_lds_dwordx4 v144, s[98:99]
	s_mov_b32 m0, s40
	s_nop 0
	global_load_lds_dwordx4 v148, s[28:29]
	s_add_i32 m0, s40, 0x2000
	s_nop 0
	global_load_lds_dwordx4 v144, s[28:29]
	s_mov_b32 m0, s68
	s_nop 0
	global_load_lds_dwordx4 v150, s[38:39]
	s_mov_b32 m0, s69
	s_nop 0
	global_load_lds_dwordx4 v146, s[38:39]
	s_waitcnt vmcnt(8)
	s_waitcnt lgkmcnt(0)
	s_barrier
	s_waitcnt lgkmcnt(0)
	v_mfma_f32_16x16x32_bf16 v[60:63], v[128:131], v[182:185], v[60:63]
	v_mfma_f32_16x16x32_bf16 v[56:59], v[136:139], v[182:185], v[56:59]
	v_mfma_f32_16x16x32_bf16 v[44:47], v[128:131], v[190:193], v[44:47]
	v_mfma_f32_16x16x32_bf16 v[40:43], v[136:139], v[190:193], v[40:43]
	v_mfma_f32_16x16x32_bf16 v[28:31], v[128:131], v[198:201], v[28:31]
	v_mfma_f32_16x16x32_bf16 v[24:27], v[136:139], v[198:201], v[24:27]
	v_mfma_f32_16x16x32_bf16 v[12:15], v[128:131], v[206:209], v[12:15]
	v_mfma_f32_16x16x32_bf16 v[8:11], v[136:139], v[206:209], v[8:11]
	v_mfma_f32_16x16x32_bf16 v[60:63], v[132:135], v[186:189], v[60:63]
	v_mfma_f32_16x16x32_bf16 v[56:59], v[140:143], v[186:189], v[56:59]
	v_mfma_f32_16x16x32_bf16 v[44:47], v[132:135], v[194:197], v[44:47]
	v_mfma_f32_16x16x32_bf16 v[40:43], v[140:143], v[194:197], v[40:43]
	v_mfma_f32_16x16x32_bf16 v[28:31], v[132:135], v[202:205], v[28:31]
	v_mfma_f32_16x16x32_bf16 v[24:27], v[140:143], v[202:205], v[24:27]
	v_mfma_f32_16x16x32_bf16 v[12:15], v[132:135], v[210:213], v[12:15]
	v_mfma_f32_16x16x32_bf16 v[8:11], v[140:143], v[210:213], v[8:11]
	v_mfma_f32_16x16x32_bf16 v[52:55], v[160:163], v[182:185], v[52:55]
	v_mfma_f32_16x16x32_bf16 v[48:51], v[174:177], v[182:185], v[48:51]
	v_mfma_f32_16x16x32_bf16 v[36:39], v[160:163], v[190:193], v[36:39]
	v_mfma_f32_16x16x32_bf16 v[32:35], v[174:177], v[190:193], v[32:35]
	v_mfma_f32_16x16x32_bf16 v[20:23], v[160:163], v[198:201], v[20:23]
	v_mfma_f32_16x16x32_bf16 v[16:19], v[174:177], v[198:201], v[16:19]
	v_mfma_f32_16x16x32_bf16 v[4:7], v[160:163], v[206:209], v[4:7]
	v_mfma_f32_16x16x32_bf16 v[0:3], v[174:177], v[206:209], v[0:3]
	v_mfma_f32_16x16x32_bf16 v[52:55], v[170:173], v[186:189], v[52:55]
	v_mfma_f32_16x16x32_bf16 v[48:51], v[178:181], v[186:189], v[48:51]
	v_mfma_f32_16x16x32_bf16 v[36:39], v[170:173], v[194:197], v[36:39]
	v_mfma_f32_16x16x32_bf16 v[32:35], v[178:181], v[194:197], v[32:35]
	v_mfma_f32_16x16x32_bf16 v[20:23], v[170:173], v[202:205], v[20:23]
	v_mfma_f32_16x16x32_bf16 v[16:19], v[178:181], v[202:205], v[16:19]
	v_mfma_f32_16x16x32_bf16 v[4:7], v[170:173], v[210:213], v[4:7]
	v_mfma_f32_16x16x32_bf16 v[0:3], v[178:181], v[210:213], v[0:3]
	s_barrier
	s_add_i32 s76, s76, 2
	s_add_u32 s74, s74, 0x100
	s_addc_u32 s75, s75, 0
	s_cmp_gt_u32 s76, 13
	s_mov_b64 s[28:29], s[36:37]
	s_cbranch_scc0 .LBB0_568
	s_and_b64 vcc, exec, s[10:11]
	s_cbranch_vccz .LBB0_571

.LBB0_615:
	v_add_u32_e32 v151, s51, v149
	ds_read_b128 v[152:155], v151
	ds_read_b128 v[156:159], v151 offset:1024
	ds_read_b128 v[160:163], v151 offset:2048
	ds_read_b128 v[164:167], v151 offset:3072
	v_add_u32_e32 v151, s56, v149
	ds_read_b128 v[168:171], v151
	ds_read_b128 v[172:175], v151 offset:1024
	ds_read_b128 v[176:179], v151 offset:2048
	ds_read_b128 v[180:183], v151 offset:3072
	s_add_u32 s38, s12, s36
	s_addc_u32 s39, s13, s37
	s_cmp_eq_u32 s63, 60
	s_cselect_b32 s42, s59, s38
	s_cselect_b32 s43, s23, s39
	s_cselect_b32 s40, s60, s61
	s_cselect_b32 s41, s21, s62
	s_add_u32 s38, s42, 0x8000
	s_addc_u32 s39, s43, 0
	s_add_i32 m0, s44, 0xc000
	ds_read_b128 v[184:187], v150
	ds_read_b128 v[188:191], v150 offset:1024
	ds_read_b128 v[192:195], v150 offset:2048
	ds_read_b128 v[196:199], v150 offset:3072
	ds_read_b128 v[200:203], v150 offset:4096
	ds_read_b128 v[204:207], v150 offset:5120
	ds_read_b128 v[208:211], v150 offset:6144
	ds_read_b128 v[212:215], v150 offset:7168
	global_load_lds_dwordx4 v146, s[12:13]
	s_add_i32 m0, s44, 0xe000
	s_nop 0
	global_load_lds_dwordx4 v144, s[12:13]
	s_waitcnt vmcnt(8)
	s_waitcnt lgkmcnt(0)
	s_barrier
	s_waitcnt lgkmcnt(0)
	v_mfma_f32_16x16x32_bf16 v[124:127], v[152:155], v[184:187], v[124:127]
	v_mfma_f32_16x16x32_bf16 v[120:123], v[160:163], v[184:187], v[120:123]
	v_mfma_f32_16x16x32_bf16 v[108:111], v[152:155], v[192:195], v[108:111]
	v_mfma_f32_16x16x32_bf16 v[104:107], v[160:163], v[192:195], v[104:107]
	v_mfma_f32_16x16x32_bf16 v[92:95], v[152:155], v[200:203], v[92:95]
	v_mfma_f32_16x16x32_bf16 v[88:91], v[160:163], v[200:203], v[88:91]
	v_mfma_f32_16x16x32_bf16 v[76:79], v[152:155], v[208:211], v[76:79]
	v_mfma_f32_16x16x32_bf16 v[72:75], v[160:163], v[208:211], v[72:75]
	v_mfma_f32_16x16x32_bf16 v[124:127], v[156:159], v[188:191], v[124:127]
	v_mfma_f32_16x16x32_bf16 v[120:123], v[164:167], v[188:191], v[120:123]
	v_mfma_f32_16x16x32_bf16 v[108:111], v[156:159], v[196:199], v[108:111]
	v_mfma_f32_16x16x32_bf16 v[104:107], v[164:167], v[196:199], v[104:107]
	v_mfma_f32_16x16x32_bf16 v[92:95], v[156:159], v[204:207], v[92:95]
	v_mfma_f32_16x16x32_bf16 v[88:91], v[164:167], v[204:207], v[88:91]
	v_mfma_f32_16x16x32_bf16 v[76:79], v[156:159], v[212:215], v[76:79]
	v_mfma_f32_16x16x32_bf16 v[72:75], v[164:167], v[212:215], v[72:75]
	v_mfma_f32_16x16x32_bf16 v[116:119], v[168:171], v[184:187], v[116:119]
	v_mfma_f32_16x16x32_bf16 v[112:115], v[176:179], v[184:187], v[112:115]
	v_mfma_f32_16x16x32_bf16 v[100:103], v[168:171], v[192:195], v[100:103]
	v_mfma_f32_16x16x32_bf16 v[96:99], v[176:179], v[192:195], v[96:99]
	v_mfma_f32_16x16x32_bf16 v[84:87], v[168:171], v[200:203], v[84:87]
	v_mfma_f32_16x16x32_bf16 v[80:83], v[176:179], v[200:203], v[80:83]
	v_mfma_f32_16x16x32_bf16 v[68:71], v[168:171], v[208:211], v[68:71]
	v_mfma_f32_16x16x32_bf16 v[64:67], v[176:179], v[208:211], v[64:67]
	v_mfma_f32_16x16x32_bf16 v[116:119], v[172:175], v[188:191], v[116:119]
	v_mfma_f32_16x16x32_bf16 v[112:115], v[180:183], v[188:191], v[112:115]
	v_mfma_f32_16x16x32_bf16 v[100:103], v[172:175], v[196:199], v[100:103]
	v_mfma_f32_16x16x32_bf16 v[96:99], v[180:183], v[196:199], v[96:99]
	v_mfma_f32_16x16x32_bf16 v[84:87], v[172:175], v[204:207], v[84:87]
	v_mfma_f32_16x16x32_bf16 v[80:83], v[180:183], v[204:207], v[80:83]
	v_mfma_f32_16x16x32_bf16 v[68:71], v[172:175], v[212:215], v[68:71]
	v_mfma_f32_16x16x32_bf16 v[64:67], v[180:183], v[212:215], v[64:67]
	s_barrier
	s_add_i32 s64, s51, s35
	s_mov_b32 m0, s64
	ds_read_b128 v[184:187], v150 offset:16384
	ds_read_b128 v[188:191], v150 offset:17408
	ds_read_b128 v[192:195], v150 offset:18432
	ds_read_b128 v[196:199], v150 offset:19456
	ds_read_b128 v[200:203], v150 offset:20480
	ds_read_b128 v[204:207], v150 offset:21504
	ds_read_b128 v[208:211], v150 offset:22528
	ds_read_b128 v[212:215], v150 offset:23552
	global_load_lds_dwordx4 v130, s[40:41]
	s_add_i32 m0, s64, 0x2000
	s_add_u32 s64, s40, 0x100000
	v_lshl_add_u64 v[218:219], s[40:41], 0, v[134:135]
	s_addc_u32 s65, s41, 0
	s_add_i32 s66, s56, s35
	global_load_lds_dwordx4 v[218:219], off
	s_mov_b32 m0, s66
	s_nop 0
	global_load_lds_dwordx4 v130, s[64:65]
	s_add_i32 m0, s66, 0x2000
	s_nop 0
	global_load_lds_dwordx4 v134, s[64:65]
	s_mov_b32 m0, s44
	s_nop 0
	global_load_lds_dwordx4 v128, s[42:43]
	s_mov_b32 m0, s45
	s_nop 0
	global_load_lds_dwordx4 v132, s[42:43]
	s_waitcnt vmcnt(8)
	s_waitcnt lgkmcnt(0)
	s_barrier
	s_waitcnt lgkmcnt(0)
	v_mfma_f32_16x16x32_bf16 v[60:63], v[152:155], v[184:187], v[60:63]
	v_mfma_f32_16x16x32_bf16 v[56:59], v[160:163], v[184:187], v[56:59]
	v_mfma_f32_16x16x32_bf16 v[44:47], v[152:155], v[192:195], v[44:47]
	v_mfma_f32_16x16x32_bf16 v[40:43], v[160:163], v[192:195], v[40:43]
	v_mfma_f32_16x16x32_bf16 v[28:31], v[152:155], v[200:203], v[28:31]
	v_mfma_f32_16x16x32_bf16 v[24:27], v[160:163], v[200:203], v[24:27]
	v_mfma_f32_16x16x32_bf16 v[12:15], v[152:155], v[208:211], v[12:15]
	v_mfma_f32_16x16x32_bf16 v[8:11], v[160:163], v[208:211], v[8:11]
	v_mfma_f32_16x16x32_bf16 v[60:63], v[156:159], v[188:191], v[60:63]
	v_mfma_f32_16x16x32_bf16 v[56:59], v[164:167], v[188:191], v[56:59]
	v_mfma_f32_16x16x32_bf16 v[44:47], v[156:159], v[196:199], v[44:47]
	v_mfma_f32_16x16x32_bf16 v[40:43], v[164:167], v[196:199], v[40:43]
	v_mfma_f32_16x16x32_bf16 v[28:31], v[156:159], v[204:207], v[28:31]
	v_mfma_f32_16x16x32_bf16 v[24:27], v[164:167], v[204:207], v[24:27]
	v_mfma_f32_16x16x32_bf16 v[12:15], v[156:159], v[212:215], v[12:15]
	v_mfma_f32_16x16x32_bf16 v[8:11], v[164:167], v[212:215], v[8:11]
	v_mfma_f32_16x16x32_bf16 v[52:55], v[168:171], v[184:187], v[52:55]
	v_mfma_f32_16x16x32_bf16 v[48:51], v[176:179], v[184:187], v[48:51]
	v_mfma_f32_16x16x32_bf16 v[36:39], v[168:171], v[192:195], v[36:39]
	v_mfma_f32_16x16x32_bf16 v[32:35], v[176:179], v[192:195], v[32:35]
	v_mfma_f32_16x16x32_bf16 v[20:23], v[168:171], v[200:203], v[20:23]
	v_mfma_f32_16x16x32_bf16 v[16:19], v[176:179], v[200:203], v[16:19]
	v_mfma_f32_16x16x32_bf16 v[4:7], v[168:171], v[208:211], v[4:7]
	v_mfma_f32_16x16x32_bf16 v[0:3], v[176:179], v[208:211], v[0:3]
	v_mfma_f32_16x16x32_bf16 v[52:55], v[172:175], v[188:191], v[52:55]
	v_mfma_f32_16x16x32_bf16 v[48:51], v[180:183], v[188:191], v[48:51]
	v_mfma_f32_16x16x32_bf16 v[36:39], v[172:175], v[196:199], v[36:39]
	v_mfma_f32_16x16x32_bf16 v[32:35], v[180:183], v[196:199], v[32:35]
	v_mfma_f32_16x16x32_bf16 v[20:23], v[172:175], v[204:207], v[20:23]
	v_mfma_f32_16x16x32_bf16 v[16:19], v[180:183], v[204:207], v[16:19]
	v_mfma_f32_16x16x32_bf16 v[4:7], v[172:175], v[212:215], v[4:7]
	v_mfma_f32_16x16x32_bf16 v[0:3], v[180:183], v[212:215], v[0:3]
	s_barrier
	s_add_i32 s64, 0, 0x18000
	v_add_u32_e32 v151, s64, v149
	s_add_i32 s65, 0, 0x1c000
	ds_read_b128 v[152:155], v151
	ds_read_b128 v[156:159], v151 offset:1024
	ds_read_b128 v[160:163], v151 offset:2048
	ds_read_b128 v[164:167], v151 offset:3072
	v_add_u32_e32 v151, s65, v149
	ds_read_b128 v[168:171], v151
	ds_read_b128 v[172:175], v151 offset:1024
	ds_read_b128 v[176:179], v151 offset:2048
	ds_read_b128 v[180:183], v151 offset:3072
	s_add_u32 s42, s42, 0x2000
	s_addc_u32 s43, s43, 0
	s_mov_b32 m0, s46
	ds_read_b128 v[184:187], v150 offset:32768
	ds_read_b128 v[188:191], v150 offset:33792
	ds_read_b128 v[192:195], v150 offset:34816
	ds_read_b128 v[196:199], v150 offset:35840
	ds_read_b128 v[200:203], v150 offset:36864
	ds_read_b128 v[204:207], v150 offset:37888
	ds_read_b128 v[208:211], v150 offset:38912
	ds_read_b128 v[212:215], v150 offset:39936
	global_load_lds_dwordx4 v128, s[42:43]
	s_mov_b32 m0, s47
	s_nop 0
	global_load_lds_dwordx4 v132, s[42:43]
	s_waitcnt vmcnt(8)
	s_waitcnt lgkmcnt(0)
	s_barrier
	s_waitcnt lgkmcnt(0)
	v_mfma_f32_16x16x32_bf16 v[124:127], v[152:155], v[184:187], v[124:127]
	v_mfma_f32_16x16x32_bf16 v[120:123], v[160:163], v[184:187], v[120:123]
	v_mfma_f32_16x16x32_bf16 v[108:111], v[152:155], v[192:195], v[108:111]
	v_mfma_f32_16x16x32_bf16 v[104:107], v[160:163], v[192:195], v[104:107]
	v_mfma_f32_16x16x32_bf16 v[92:95], v[152:155], v[200:203], v[92:95]
	v_mfma_f32_16x16x32_bf16 v[88:91], v[160:163], v[200:203], v[88:91]
	v_mfma_f32_16x16x32_bf16 v[76:79], v[152:155], v[208:211], v[76:79]
	v_mfma_f32_16x16x32_bf16 v[72:75], v[160:163], v[208:211], v[72:75]
	v_mfma_f32_16x16x32_bf16 v[124:127], v[156:159], v[188:191], v[124:127]
	v_mfma_f32_16x16x32_bf16 v[120:123], v[164:167], v[188:191], v[120:123]
	v_mfma_f32_16x16x32_bf16 v[108:111], v[156:159], v[196:199], v[108:111]
	v_mfma_f32_16x16x32_bf16 v[104:107], v[164:167], v[196:199], v[104:107]
	v_mfma_f32_16x16x32_bf16 v[92:95], v[156:159], v[204:207], v[92:95]
	v_mfma_f32_16x16x32_bf16 v[88:91], v[164:167], v[204:207], v[88:91]
	v_mfma_f32_16x16x32_bf16 v[76:79], v[156:159], v[212:215], v[76:79]
	v_mfma_f32_16x16x32_bf16 v[72:75], v[164:167], v[212:215], v[72:75]
	v_mfma_f32_16x16x32_bf16 v[116:119], v[168:171], v[184:187], v[116:119]
	v_mfma_f32_16x16x32_bf16 v[112:115], v[176:179], v[184:187], v[112:115]
	v_mfma_f32_16x16x32_bf16 v[100:103], v[168:171], v[192:195], v[100:103]
	v_mfma_f32_16x16x32_bf16 v[96:99], v[176:179], v[192:195], v[96:99]
	v_mfma_f32_16x16x32_bf16 v[84:87], v[168:171], v[200:203], v[84:87]
	v_mfma_f32_16x16x32_bf16 v[80:83], v[176:179], v[200:203], v[80:83]
	v_mfma_f32_16x16x32_bf16 v[68:71], v[168:171], v[208:211], v[68:71]
	v_mfma_f32_16x16x32_bf16 v[64:67], v[176:179], v[208:211], v[64:67]
	v_mfma_f32_16x16x32_bf16 v[116:119], v[172:175], v[188:191], v[116:119]
	v_mfma_f32_16x16x32_bf16 v[112:115], v[180:183], v[188:191], v[112:115]
	v_mfma_f32_16x16x32_bf16 v[100:103], v[172:175], v[196:199], v[100:103]
	v_mfma_f32_16x16x32_bf16 v[96:99], v[180:183], v[196:199], v[96:99]
	v_mfma_f32_16x16x32_bf16 v[84:87], v[172:175], v[204:207], v[84:87]
	v_mfma_f32_16x16x32_bf16 v[80:83], v[180:183], v[204:207], v[80:83]
	v_mfma_f32_16x16x32_bf16 v[68:71], v[172:175], v[212:215], v[68:71]
	v_mfma_f32_16x16x32_bf16 v[64:67], v[180:183], v[212:215], v[64:67]
	s_barrier
	s_add_u32 s98, s40, s16
	s_addc_u32 s99, s41, s17
	s_add_i32 s42, s64, s35
	s_mov_b32 m0, s42
	ds_read_b128 v[184:187], v150 offset:49152
	ds_read_b128 v[188:191], v150 offset:50176
	ds_read_b128 v[192:195], v150 offset:51200
	ds_read_b128 v[196:199], v150 offset:52224
	ds_read_b128 v[200:203], v150 offset:53248
	ds_read_b128 v[204:207], v150 offset:54272
	ds_read_b128 v[208:211], v150 offset:55296
	ds_read_b128 v[212:215], v150 offset:56320
	global_load_lds_dwordx4 v130, s[98:99]
	s_add_i32 m0, s42, 0x2000
	s_add_u32 s40, s40, 0x100080
	v_lshl_add_u64 v[216:217], v[218:219], 0, s[16:17]
	s_addc_u32 s41, s41, 0
	s_add_i32 s42, s65, s35
	global_load_lds_dwordx4 v[216:217], off
	s_mov_b32 m0, s42
	s_nop 0
	global_load_lds_dwordx4 v130, s[40:41]
	s_add_i32 m0, s42, 0x2000
	s_nop 0
	global_load_lds_dwordx4 v134, s[40:41]
	s_mov_b32 m0, s48
	s_nop 0
	global_load_lds_dwordx4 v128, s[38:39]
	s_mov_b32 m0, s49
	s_nop 0
	global_load_lds_dwordx4 v132, s[38:39]
	s_waitcnt vmcnt(8)
	s_waitcnt lgkmcnt(0)
	s_barrier
	s_waitcnt lgkmcnt(0)
	v_mfma_f32_16x16x32_bf16 v[60:63], v[152:155], v[184:187], v[60:63]
	v_mfma_f32_16x16x32_bf16 v[56:59], v[160:163], v[184:187], v[56:59]
	v_mfma_f32_16x16x32_bf16 v[44:47], v[152:155], v[192:195], v[44:47]
	v_mfma_f32_16x16x32_bf16 v[40:43], v[160:163], v[192:195], v[40:43]
	v_mfma_f32_16x16x32_bf16 v[28:31], v[152:155], v[200:203], v[28:31]
	v_mfma_f32_16x16x32_bf16 v[24:27], v[160:163], v[200:203], v[24:27]
	v_mfma_f32_16x16x32_bf16 v[12:15], v[152:155], v[208:211], v[12:15]
	v_mfma_f32_16x16x32_bf16 v[8:11], v[160:163], v[208:211], v[8:11]
	v_mfma_f32_16x16x32_bf16 v[60:63], v[156:159], v[188:191], v[60:63]
	v_mfma_f32_16x16x32_bf16 v[56:59], v[164:167], v[188:191], v[56:59]
	v_mfma_f32_16x16x32_bf16 v[44:47], v[156:159], v[196:199], v[44:47]
	v_mfma_f32_16x16x32_bf16 v[40:43], v[164:167], v[196:199], v[40:43]
	v_mfma_f32_16x16x32_bf16 v[28:31], v[156:159], v[204:207], v[28:31]
	v_mfma_f32_16x16x32_bf16 v[24:27], v[164:167], v[204:207], v[24:27]
	v_mfma_f32_16x16x32_bf16 v[12:15], v[156:159], v[212:215], v[12:15]
	v_mfma_f32_16x16x32_bf16 v[8:11], v[164:167], v[212:215], v[8:11]
	v_mfma_f32_16x16x32_bf16 v[52:55], v[168:171], v[184:187], v[52:55]
	v_mfma_f32_16x16x32_bf16 v[48:51], v[176:179], v[184:187], v[48:51]
	v_mfma_f32_16x16x32_bf16 v[36:39], v[168:171], v[192:195], v[36:39]
	v_mfma_f32_16x16x32_bf16 v[32:35], v[176:179], v[192:195], v[32:35]
	v_mfma_f32_16x16x32_bf16 v[20:23], v[168:171], v[200:203], v[20:23]
	v_mfma_f32_16x16x32_bf16 v[16:19], v[176:179], v[200:203], v[16:19]
	v_mfma_f32_16x16x32_bf16 v[4:7], v[168:171], v[208:211], v[4:7]
	v_mfma_f32_16x16x32_bf16 v[0:3], v[176:179], v[208:211], v[0:3]
	v_mfma_f32_16x16x32_bf16 v[52:55], v[172:175], v[188:191], v[52:55]
	v_mfma_f32_16x16x32_bf16 v[48:51], v[180:183], v[188:191], v[48:51]
	v_mfma_f32_16x16x32_bf16 v[36:39], v[172:175], v[196:199], v[36:39]
	v_mfma_f32_16x16x32_bf16 v[32:35], v[180:183], v[196:199], v[32:35]
	v_mfma_f32_16x16x32_bf16 v[20:23], v[172:175], v[204:207], v[20:23]
	v_mfma_f32_16x16x32_bf16 v[16:19], v[180:183], v[204:207], v[16:19]
	v_mfma_f32_16x16x32_bf16 v[4:7], v[172:175], v[212:215], v[4:7]
	v_mfma_f32_16x16x32_bf16 v[0:3], v[180:183], v[212:215], v[0:3]
	s_barrier
	s_add_i32 s63, s63, 2
	s_add_u32 s61, s61, 0x100
	s_addc_u32 s62, s62, 0
	s_add_u32 s36, s36, 0x10000
	s_addc_u32 s37, s37, 0
	v_lshl_add_u64 v[146:147], v[146:147], 0, s[18:19]
	s_cmp_gt_u32 s63, 61
	v_lshl_add_u64 v[144:145], v[144:145], 0, s[18:19]
	s_cbranch_scc0 .LBB0_615
	s_andn2_b64 vcc, exec, s[4:5]
	s_cbranch_vccnz .LBB0_607
	v_mov_b32_e32 v0, 0
	s_mov_b32 s8, s20
	s_mov_b32 s6, s22
	s_mov_b64 s[10:11], s[28:29]
	s_mov_b64 s[12:13], s[26:27]
	s_mov_b32 s50, s57
	v_mov_b32_e32 v1, v0
	v_mov_b32_e32 v2, v0
	v_mov_b32_e32 v3, v0
	v_mov_b32_e32 v4, v0
	v_mov_b32_e32 v5, v0
	v_mov_b32_e32 v6, v0
	v_mov_b32_e32 v7, v0
	v_mov_b32_e32 v16, v0
	v_mov_b32_e32 v17, v0
	v_mov_b32_e32 v18, v0
	v_mov_b32_e32 v19, v0
	v_mov_b32_e32 v20, v0
	v_mov_b32_e32 v21, v0
	v_mov_b32_e32 v22, v0
	v_mov_b32_e32 v23, v0
	v_mov_b32_e32 v32, v0
	v_mov_b32_e32 v33, v0
	v_mov_b32_e32 v34, v0
	v_mov_b32_e32 v35, v0
	v_mov_b32_e32 v36, v0
	v_mov_b32_e32 v37, v0
	v_mov_b32_e32 v38, v0
	v_mov_b32_e32 v39, v0
	v_mov_b32_e32 v48, v0
	v_mov_b32_e32 v49, v0
	v_mov_b32_e32 v50, v0
	v_mov_b32_e32 v51, v0
	v_mov_b32_e32 v52, v0
	v_mov_b32_e32 v53, v0
	v_mov_b32_e32 v54, v0
	v_mov_b32_e32 v55, v0
	v_mov_b32_e32 v8, v0
	v_mov_b32_e32 v9, v0
	v_mov_b32_e32 v10, v0
	v_mov_b32_e32 v11, v0
	v_mov_b32_e32 v12, v0
	v_mov_b32_e32 v13, v0
	v_mov_b32_e32 v14, v0
	v_mov_b32_e32 v15, v0
	v_mov_b32_e32 v24, v0
	v_mov_b32_e32 v25, v0
	v_mov_b32_e32 v26, v0
	v_mov_b32_e32 v27, v0
	v_mov_b32_e32 v28, v0
	v_mov_b32_e32 v29, v0
	v_mov_b32_e32 v30, v0
	v_mov_b32_e32 v31, v0
	v_mov_b32_e32 v40, v0
	v_mov_b32_e32 v41, v0
	v_mov_b32_e32 v42, v0
	v_mov_b32_e32 v43, v0
	v_mov_b32_e32 v44, v0
	v_mov_b32_e32 v45, v0
	v_mov_b32_e32 v46, v0
	v_mov_b32_e32 v47, v0
	v_mov_b32_e32 v56, v0
	v_mov_b32_e32 v57, v0
	v_mov_b32_e32 v58, v0
	v_mov_b32_e32 v59, v0
	v_mov_b32_e32 v60, v0
	v_mov_b32_e32 v61, v0
	v_mov_b32_e32 v62, v0
	v_mov_b32_e32 v63, v0
	v_mov_b32_e32 v64, v0
	v_mov_b32_e32 v65, v0
	v_mov_b32_e32 v66, v0
	v_mov_b32_e32 v67, v0
	v_mov_b32_e32 v68, v0
	v_mov_b32_e32 v69, v0
	v_mov_b32_e32 v70, v0
	v_mov_b32_e32 v71, v0
	v_mov_b32_e32 v80, v0
	v_mov_b32_e32 v81, v0
	v_mov_b32_e32 v82, v0
	v_mov_b32_e32 v83, v0
	v_mov_b32_e32 v84, v0
	v_mov_b32_e32 v85, v0
	v_mov_b32_e32 v86, v0
	v_mov_b32_e32 v87, v0
	v_mov_b32_e32 v96, v0
	v_mov_b32_e32 v97, v0
	v_mov_b32_e32 v98, v0
	v_mov_b32_e32 v99, v0
	v_mov_b32_e32 v100, v0
	v_mov_b32_e32 v101, v0
	v_mov_b32_e32 v102, v0
	v_mov_b32_e32 v103, v0
	v_mov_b32_e32 v112, v0
	v_mov_b32_e32 v113, v0
	v_mov_b32_e32 v114, v0
	v_mov_b32_e32 v115, v0
	v_mov_b32_e32 v116, v0
	v_mov_b32_e32 v117, v0
	v_mov_b32_e32 v118, v0
	v_mov_b32_e32 v119, v0
	v_mov_b32_e32 v72, v0
	v_mov_b32_e32 v73, v0
	v_mov_b32_e32 v74, v0
	v_mov_b32_e32 v75, v0
	v_mov_b32_e32 v76, v0
	v_mov_b32_e32 v77, v0
	v_mov_b32_e32 v78, v0
	v_mov_b32_e32 v79, v0
	v_mov_b32_e32 v88, v0
	v_mov_b32_e32 v89, v0
	v_mov_b32_e32 v90, v0
	v_mov_b32_e32 v91, v0
	v_mov_b32_e32 v92, v0
	v_mov_b32_e32 v93, v0
	v_mov_b32_e32 v94, v0
	v_mov_b32_e32 v95, v0
	v_mov_b32_e32 v104, v0
	v_mov_b32_e32 v105, v0
	v_mov_b32_e32 v106, v0
	v_mov_b32_e32 v107, v0
	v_mov_b32_e32 v108, v0
	v_mov_b32_e32 v109, v0
	v_mov_b32_e32 v110, v0
	v_mov_b32_e32 v111, v0
	v_mov_b32_e32 v120, v0
	v_mov_b32_e32 v121, v0
	v_mov_b32_e32 v122, v0
	v_mov_b32_e32 v123, v0
	v_mov_b32_e32 v124, v0
	v_mov_b32_e32 v125, v0
	v_mov_b32_e32 v126, v0
	v_mov_b32_e32 v127, v0
	s_branch .LBB0_607
